# combined: residual-epilogue loads hoisted ahead of stores (odd/even out-proj), up-epilogue dead DPP inits removed, scan LDS fragment reuse, on top of GEMM half re-alignment
# speedup vs baseline: 1.0067x; 1.0067x over previous
;     __device__ __forceinline__ void operator()(const f32x4 (&acc)[2][2][4][2], const Unit& u, int wr, int wc, int fr, int fq) const {
;         const int row0 = u.pm * BM + wr * 64 + fr, col0 = u.pn * BM + wc * 32 + 4 * fq;
;         h16x4 hin[2][2], hnx[2][2];
; #pragma unroll
;         for (int bj = 0; bj < 2; ++bj)
; #pragma unroll
;             for (int n = 0; n < 2; ++n) hin[bj][n] = *(const h16x4*)(HB + (size_t)row0 * D + col0 + bj * HALF + n * 16);
; #pragma unroll
;         for (int g = 0; g < 8; ++g) {
;             const int ai = g >> 2, m = g & 3;
;             const int r = row0 + ai * HALF + m * 16; float ss = 0.f;
;             if (g < 7) { const int rn = row0 + ((g + 1) >> 2) * HALF + ((g + 1) & 3) * 16;
; #pragma unroll
;                 for (int bj = 0; bj < 2; ++bj)
; #pragma unroll
;                     for (int n = 0; n < 2; ++n) hnx[bj][n] = *(const h16x4*)(HB + (size_t)rn * D + col0 + bj * HALF + n * 16); }
; #pragma unroll
;             for (int bj = 0; bj < 2; ++bj)
; #pragma unroll
;                 for (int n = 0; n < 2; ++n) {
;                     const size_t o = (size_t)r * D + col0 + bj * HALF + n * 16;
;                     f32x4 hv; hv[0] = (float)hin[bj][n][0]; hv[1] = (float)hin[bj][n][1]; hv[2] = (float)hin[bj][n][2]; hv[3] = (float)hin[bj][n][3];
;                     hv += acc[ai][bj][m][n];
;                     ss += hv[0] * hv[0] + hv[1] * hv[1] + hv[2] * hv[2] + hv[3] * hv[3];
;                     if (OUT != nullptr) *(f32x4*)(OUT + o) = hv;
;                     else { h16x4 hh; hh[0] = (h16)hv[0]; hh[1] = (h16)hv[1]; hh[2] = (h16)hv[2]; hh[3] = (h16)hv[3]; *(h16x4*)(HB + o) = hh; }
;                 }
;             ss += __shfl_xor(ss, 16); ss += __shfl_xor(ss, 32);
;             if (fq == 0) atomicAdd(rsq_next + r, ss);
.Lalign_oddout_a:
	v_lshl_add_u32 v138, s45, 8, v154
	v_lshl_or_b32 v136, s44, 8, v163
	v_ashrrev_i32_e32 v139, 31, v138
	v_lshlrev_b64 v[140:141], 11, v[138:139]
	v_ashrrev_i32_e32 v137, 31, v136
	v_lshl_add_u64 v[140:141], s[12:13], 0, v[140:141]
	v_lshlrev_b64 v[142:143], 1, v[136:137]
	v_lshl_add_u64 v[152:153], v[140:141], 0, v[142:143]
	global_load_dwordx2 v[166:167], v[152:153], off
	global_load_dwordx2 v[168:169], v[152:153], off offset:32
	global_load_dwordx2 v[170:171], v[152:153], off offset:256
	global_load_dwordx2 v[172:173], v[152:153], off offset:288
	v_or_b32_e32 v140, 16, v138
	v_ashrrev_i32_e32 v141, 31, v140
	v_lshlrev_b64 v[144:145], 11, v[140:141]
	v_lshl_add_u64 v[144:145], s[12:13], 0, v[144:145]
	v_lshl_add_u64 v[142:143], v[144:145], 0, v[142:143]
	global_load_dwordx2 v[150:151], v[142:143], off
	global_load_dwordx2 v[148:149], v[142:143], off offset:32
	global_load_dwordx2 v[146:147], v[142:143], off offset:256
	global_load_dwordx2 v[144:145], v[142:143], off offset:288
	v_lshlrev_b32_e32 v242, 11, v138
	v_lshl_add_u32 v242, v136, 1, v242
	v_add_u32_e32 v243, 0x10000, v242
	global_load_dwordx2 v[176:177], v243, s[12:13]
	global_load_dwordx2 v[178:179], v243, s[12:13] offset:32
	global_load_dwordx2 v[180:181], v243, s[12:13] offset:256
	global_load_dwordx2 v[182:183], v243, s[12:13] offset:288
	v_add_u32_e32 v243, 0x18000, v242
	global_load_dwordx2 v[184:185], v243, s[12:13]
	global_load_dwordx2 v[186:187], v243, s[12:13] offset:32
	global_load_dwordx2 v[188:189], v243, s[12:13] offset:256
	global_load_dwordx2 v[190:191], v243, s[12:13] offset:288
	v_add_u32_e32 v243, 0x40000, v242
	global_load_dwordx2 v[192:193], v243, s[12:13]
	global_load_dwordx2 v[194:195], v243, s[12:13] offset:32
	global_load_dwordx2 v[196:197], v243, s[12:13] offset:256
	global_load_dwordx2 v[198:199], v243, s[12:13] offset:288
	v_add_u32_e32 v243, 0x48000, v242
	global_load_dwordx2 v[200:201], v243, s[12:13]
	global_load_dwordx2 v[202:203], v243, s[12:13] offset:32
	global_load_dwordx2 v[204:205], v243, s[12:13] offset:256
	global_load_dwordx2 v[206:207], v243, s[12:13] offset:288
	v_add_u32_e32 v243, 0x50000, v242
	global_load_dwordx2 v[208:209], v243, s[12:13]
	global_load_dwordx2 v[210:211], v243, s[12:13] offset:32
	global_load_dwordx2 v[212:213], v243, s[12:13] offset:256
	global_load_dwordx2 v[232:233], v243, s[12:13] offset:288
	v_add_u32_e32 v243, 0x58000, v242
	global_load_dwordx2 v[234:235], v243, s[12:13]
	global_load_dwordx2 v[236:237], v243, s[12:13] offset:32
	global_load_dwordx2 v[238:239], v243, s[12:13] offset:256
	global_load_dwordx2 v[240:241], v243, s[12:13] offset:288
	s_waitcnt vmcnt(24)
	v_cvt_f32_f16_e32 v174, v166
	v_cvt_f32_f16_sdwa v175, v166 dst_sel:DWORD dst_unused:UNUSED_PAD src0_sel:WORD_1
	v_cvt_f32_f16_e32 v166, v167
	v_cvt_f32_f16_sdwa v167, v167 dst_sel:DWORD dst_unused:UNUSED_PAD src0_sel:WORD_1
	v_pk_add_f32 v[126:127], v[126:127], v[174:175]
	s_nop 0
	v_mul_f32_e32 v165, v127, v127
	v_pk_add_f32 v[128:129], v[128:129], v[166:167]
	v_fmac_f32_e32 v165, v126, v126
	v_fmac_f32_e32 v165, v128, v128
	v_fmac_f32_e32 v165, v129, v129
	v_cvt_pk_f16_f32 v129, v128, v129
	v_cvt_pk_f16_f32 v128, v126, v127
	v_cvt_f32_f16_e32 v126, v168
	v_cvt_f32_f16_sdwa v127, v168 dst_sel:DWORD dst_unused:UNUSED_PAD src0_sel:WORD_1
	global_store_dwordx2 v[152:153], v[128:129], off
	v_cvt_f32_f16_e32 v128, v169
	v_cvt_f32_f16_sdwa v129, v169 dst_sel:DWORD dst_unused:UNUSED_PAD src0_sel:WORD_1
	v_pk_add_f32 v[122:123], v[122:123], v[126:127]
	v_pk_add_f32 v[124:125], v[124:125], v[128:129]
	v_mul_f32_e32 v126, v123, v123
	v_fmac_f32_e32 v126, v122, v122
	v_fmac_f32_e32 v126, v124, v124
	v_fmac_f32_e32 v126, v125, v125
	v_cvt_pk_f16_f32 v125, v124, v125
	v_cvt_pk_f16_f32 v124, v122, v123
	v_cvt_f32_f16_e32 v122, v170
	v_cvt_f32_f16_sdwa v123, v170 dst_sel:DWORD dst_unused:UNUSED_PAD src0_sel:WORD_1
	global_store_dwordx2 v[152:153], v[124:125], off offset:32
	v_cvt_f32_f16_e32 v124, v171
	v_cvt_f32_f16_sdwa v125, v171 dst_sel:DWORD dst_unused:UNUSED_PAD src0_sel:WORD_1
	v_pk_add_f32 v[118:119], v[118:119], v[122:123]
	v_add_f32_e32 v126, v165, v126
	v_mul_f32_e32 v122, v119, v119
	v_pk_add_f32 v[120:121], v[120:121], v[124:125]
	v_fmac_f32_e32 v122, v118, v118
	v_fmac_f32_e32 v122, v120, v120
	v_fmac_f32_e32 v122, v121, v121
	v_cvt_pk_f16_f32 v121, v120, v121
	v_cvt_pk_f16_f32 v120, v118, v119
	v_cvt_f32_f16_e32 v118, v172
	v_cvt_f32_f16_sdwa v119, v172 dst_sel:DWORD dst_unused:UNUSED_PAD src0_sel:WORD_1
	global_store_dwordx2 v[152:153], v[120:121], off offset:256
	v_cvt_f32_f16_e32 v120, v173
	v_cvt_f32_f16_sdwa v121, v173 dst_sel:DWORD dst_unused:UNUSED_PAD src0_sel:WORD_1
	v_pk_add_f32 v[114:115], v[114:115], v[118:119]
	v_add_f32_e32 v122, v126, v122
	v_mul_f32_e32 v118, v115, v115
	v_pk_add_f32 v[116:117], v[116:117], v[120:121]
	v_fmac_f32_e32 v118, v114, v114
	v_fmac_f32_e32 v118, v116, v116
	v_fmac_f32_e32 v118, v117, v117
	v_add_f32_e32 v118, v122, v118
	v_cvt_pk_f16_f32 v117, v116, v117
	v_cvt_pk_f16_f32 v116, v114, v115
	ds_bpermute_b32 v114, v161, v118
	global_store_dwordx2 v[152:153], v[116:117], off offset:288
	s_waitcnt lgkmcnt(0)
	v_add_f32_e32 v114, v118, v114
	ds_bpermute_b32 v115, v162, v114
	s_and_saveexec_b64 s[4:5], s[8:9]
	s_cbranch_execz .LBB0_798
	v_lshl_add_u64 v[116:117], v[138:139], 2, s[14:15]
	s_waitcnt lgkmcnt(0)
	v_add_f32_e32 v114, v114, v115
	global_atomic_add_f32 v[116:117], v114, off
;     __device__ __forceinline__ void operator()(const f32x4 (&acc)[2][2][4][2], const Unit& u, int wr, int wc, int fr, int fq) const {
;     ...
; #pragma unroll
;         for (int g = 0; g < 8; ++g) {
;             const int ai = g >> 2, m = g & 3;
;             const int r = row0 + ai * HALF + m * 16; float ss = 0.f;
;             if (g < 7) { const int rn = row0 + ((g + 1) >> 2) * HALF + ((g + 1) & 3) * 16;
; #pragma unroll
;                 for (int bj = 0; bj < 2; ++bj)
; #pragma unroll
;                     for (int n = 0; n < 2; ++n) hnx[bj][n] = *(const h16x4*)(HB + (size_t)rn * D + col0 + bj * HALF + n * 16); }
; #pragma unroll
;             for (int bj = 0; bj < 2; ++bj)
; #pragma unroll
;                 for (int n = 0; n < 2; ++n) {
;                     const size_t o = (size_t)r * D + col0 + bj * HALF + n * 16;
;                     f32x4 hv; hv[0] = (float)hin[bj][n][0]; hv[1] = (float)hin[bj][n][1]; hv[2] = (float)hin[bj][n][2]; hv[3] = (float)hin[bj][n][3];
;                     hv += acc[ai][bj][m][n];
;                     ss += hv[0] * hv[0] + hv[1] * hv[1] + hv[2] * hv[2] + hv[3] * hv[3];
;                     if (OUT != nullptr) *(f32x4*)(OUT + o) = hv;
;                     else { h16x4 hh; hh[0] = (h16)hv[0]; hh[1] = (h16)hv[1]; hh[2] = (h16)hv[2]; hh[3] = (h16)hv[3]; *(h16x4*)(HB + o) = hh; }
;                 }
;             ss += __shfl_xor(ss, 16); ss += __shfl_xor(ss, 32);
;             if (fq == 0) atomicAdd(rsq_next + r, ss);
.LBB0_798:
	s_or_b64 exec, exec, s[4:5]
	v_or_b32_e32 v114, 32, v138
	s_waitcnt lgkmcnt(0)
	v_ashrrev_i32_e32 v115, 31, v114
	v_lshlrev_b64 v[116:117], 11, v[114:115]
	v_lshl_add_u64 v[116:117], s[12:13], 0, v[116:117]
	v_lshl_add_u64 v[116:117], v[136:137], 1, v[116:117]
	s_waitcnt vmcnt(25)
	v_mov_b32_e32 v124, v176
	v_mov_b32_e32 v125, v177
	v_mov_b32_e32 v122, v178
	v_mov_b32_e32 v123, v179
	v_mov_b32_e32 v120, v180
	v_mov_b32_e32 v121, v181
	v_mov_b32_e32 v118, v182
	v_mov_b32_e32 v119, v183
	v_cvt_f32_f16_sdwa v127, v150 dst_sel:DWORD dst_unused:UNUSED_PAD src0_sel:WORD_1
	v_cvt_f32_f16_e32 v126, v150
	v_cvt_f32_f16_sdwa v129, v151 dst_sel:DWORD dst_unused:UNUSED_PAD src0_sel:WORD_1
	v_cvt_f32_f16_e32 v128, v151
	v_pk_add_f32 v[110:111], v[110:111], v[126:127]
	s_nop 0
	v_mul_f32_e32 v139, v111, v111
	v_pk_add_f32 v[112:113], v[112:113], v[128:129]
	v_fmac_f32_e32 v139, v110, v110
	v_fmac_f32_e32 v139, v112, v112
	v_fmac_f32_e32 v139, v113, v113
	v_cvt_pk_f16_f32 v113, v112, v113
	v_cvt_f32_f16_sdwa v127, v148 dst_sel:DWORD dst_unused:UNUSED_PAD src0_sel:WORD_1
	v_cvt_f32_f16_e32 v126, v148
	v_cvt_pk_f16_f32 v112, v110, v111
	v_cvt_f32_f16_sdwa v111, v146 dst_sel:DWORD dst_unused:UNUSED_PAD src0_sel:WORD_1
	v_cvt_f32_f16_e32 v110, v146
	v_cvt_f32_f16_sdwa v129, v149 dst_sel:DWORD dst_unused:UNUSED_PAD src0_sel:WORD_1
	v_cvt_f32_f16_e32 v128, v149
	global_store_dwordx2 v[142:143], v[112:113], off
	v_cvt_f32_f16_sdwa v113, v147 dst_sel:DWORD dst_unused:UNUSED_PAD src0_sel:WORD_1
	v_cvt_f32_f16_e32 v112, v147
	v_pk_add_f32 v[106:107], v[106:107], v[126:127]
	v_pk_add_f32 v[102:103], v[102:103], v[110:111]
	v_cvt_f32_f16_sdwa v111, v144 dst_sel:DWORD dst_unused:UNUSED_PAD src0_sel:WORD_1
	v_cvt_f32_f16_e32 v110, v144
	v_mul_f32_e32 v126, v107, v107
	v_pk_add_f32 v[108:109], v[108:109], v[128:129]
	v_fmac_f32_e32 v126, v106, v106
	v_pk_add_f32 v[104:105], v[104:105], v[112:113]
	v_cvt_f32_f16_sdwa v113, v145 dst_sel:DWORD dst_unused:UNUSED_PAD src0_sel:WORD_1
	v_cvt_f32_f16_e32 v112, v145
	v_fmac_f32_e32 v126, v108, v108
	v_fmac_f32_e32 v126, v109, v109
	v_cvt_pk_f16_f32 v109, v108, v109
	v_mul_f32_e32 v108, v103, v103
	v_pk_add_f32 v[110:111], v[98:99], v[110:111]
	v_fmac_f32_e32 v108, v102, v102
	v_mul_f32_e32 v98, v111, v111
	v_fmac_f32_e32 v108, v104, v104
	v_pk_add_f32 v[100:101], v[100:101], v[112:113]
	v_fmac_f32_e32 v98, v110, v110
	v_add_f32_e32 v126, v139, v126
	v_fmac_f32_e32 v108, v105, v105
	v_fmac_f32_e32 v98, v100, v100
	v_add_f32_e32 v108, v126, v108
	v_fmac_f32_e32 v98, v101, v101
	v_add_f32_e32 v98, v108, v98
	ds_bpermute_b32 v99, v161, v98
	v_cvt_pk_f16_f32 v108, v106, v107
	v_cvt_pk_f16_f32 v105, v104, v105
	v_cvt_pk_f16_f32 v104, v102, v103
	v_cvt_pk_f16_f32 v101, v100, v101
	s_waitcnt lgkmcnt(0)
	v_add_f32_e32 v98, v98, v99
	ds_bpermute_b32 v99, v162, v98
	v_cvt_pk_f16_f32 v100, v110, v111
	global_store_dwordx2 v[142:143], v[108:109], off offset:32
	global_store_dwordx2 v[142:143], v[104:105], off offset:256
	global_store_dwordx2 v[142:143], v[100:101], off offset:288
	s_and_saveexec_b64 s[4:5], s[8:9]
	s_cbranch_execz .LBB0_800
	v_lshl_add_u64 v[100:101], v[140:141], 2, s[14:15]
	s_waitcnt lgkmcnt(0)
	v_add_f32_e32 v98, v98, v99
	global_atomic_add_f32 v[100:101], v98, off
.LBB0_800:
	s_or_b64 exec, exec, s[4:5]
	v_or_b32_e32 v98, 48, v138
	s_waitcnt lgkmcnt(0)
	v_ashrrev_i32_e32 v99, 31, v98
	v_lshlrev_b64 v[100:101], 11, v[98:99]
	v_lshl_add_u64 v[100:101], s[12:13], 0, v[100:101]
	v_lshl_add_u64 v[100:101], v[136:137], 1, v[100:101]
	s_waitcnt vmcnt(26)
	v_mov_b32_e32 v108, v184
	v_mov_b32_e32 v109, v185
	v_mov_b32_e32 v106, v186
	v_mov_b32_e32 v107, v187
	v_mov_b32_e32 v104, v188
	v_mov_b32_e32 v105, v189
	v_mov_b32_e32 v102, v190
	v_mov_b32_e32 v103, v191
	s_nop 0
	v_cvt_f32_f16_sdwa v111, v124 dst_sel:DWORD dst_unused:UNUSED_PAD src0_sel:WORD_1
	v_cvt_f32_f16_e32 v110, v124
	v_cvt_f32_f16_sdwa v113, v125 dst_sel:DWORD dst_unused:UNUSED_PAD src0_sel:WORD_1
	v_cvt_f32_f16_e32 v112, v125
	v_pk_add_f32 v[94:95], v[94:95], v[110:111]
	s_nop 0
	v_mul_f32_e32 v124, v95, v95
	v_pk_add_f32 v[96:97], v[96:97], v[112:113]
	v_fmac_f32_e32 v124, v94, v94
	v_fmac_f32_e32 v124, v96, v96
	v_fmac_f32_e32 v124, v97, v97
	v_cvt_pk_f16_f32 v97, v96, v97
	s_nop 0
	v_cvt_f32_f16_sdwa v111, v122 dst_sel:DWORD dst_unused:UNUSED_PAD src0_sel:WORD_1
	v_cvt_f32_f16_e32 v110, v122
	v_cvt_pk_f16_f32 v96, v94, v95
	s_nop 0
	v_cvt_f32_f16_sdwa v95, v120 dst_sel:DWORD dst_unused:UNUSED_PAD src0_sel:WORD_1
	v_cvt_f32_f16_e32 v94, v120
	v_cvt_f32_f16_sdwa v113, v123 dst_sel:DWORD dst_unused:UNUSED_PAD src0_sel:WORD_1
	v_cvt_f32_f16_e32 v112, v123
	global_store_dwordx2 v[116:117], v[96:97], off
	v_cvt_f32_f16_sdwa v97, v121 dst_sel:DWORD dst_unused:UNUSED_PAD src0_sel:WORD_1
	v_cvt_f32_f16_e32 v96, v121
	v_pk_add_f32 v[90:91], v[90:91], v[110:111]
	v_pk_add_f32 v[86:87], v[86:87], v[94:95]
	s_nop 0
	v_cvt_f32_f16_sdwa v95, v118 dst_sel:DWORD dst_unused:UNUSED_PAD src0_sel:WORD_1
	v_cvt_f32_f16_e32 v94, v118
	v_mul_f32_e32 v110, v91, v91
	v_pk_add_f32 v[92:93], v[92:93], v[112:113]
	v_fmac_f32_e32 v110, v90, v90
	v_pk_add_f32 v[88:89], v[88:89], v[96:97]
	v_cvt_f32_f16_sdwa v97, v119 dst_sel:DWORD dst_unused:UNUSED_PAD src0_sel:WORD_1
	v_cvt_f32_f16_e32 v96, v119
	v_fmac_f32_e32 v110, v92, v92
	v_fmac_f32_e32 v110, v93, v93
	v_cvt_pk_f16_f32 v93, v92, v93
	v_mul_f32_e32 v92, v87, v87
	v_pk_add_f32 v[94:95], v[82:83], v[94:95]
	v_fmac_f32_e32 v92, v86, v86
	v_mul_f32_e32 v82, v95, v95
	v_fmac_f32_e32 v92, v88, v88
	v_pk_add_f32 v[84:85], v[84:85], v[96:97]
	v_fmac_f32_e32 v82, v94, v94
	v_add_f32_e32 v110, v124, v110
	v_fmac_f32_e32 v92, v89, v89
	v_fmac_f32_e32 v82, v84, v84
	v_add_f32_e32 v92, v110, v92
	v_fmac_f32_e32 v82, v85, v85
	v_add_f32_e32 v82, v92, v82
	ds_bpermute_b32 v83, v161, v82
	v_cvt_pk_f16_f32 v92, v90, v91
	v_cvt_pk_f16_f32 v89, v88, v89
	v_cvt_pk_f16_f32 v88, v86, v87
	v_cvt_pk_f16_f32 v85, v84, v85
	s_waitcnt lgkmcnt(0)
	v_add_f32_e32 v82, v82, v83
	ds_bpermute_b32 v83, v162, v82
	v_cvt_pk_f16_f32 v84, v94, v95
	global_store_dwordx2 v[116:117], v[92:93], off offset:32
	global_store_dwordx2 v[116:117], v[88:89], off offset:256
	global_store_dwordx2 v[116:117], v[84:85], off offset:288
	s_and_saveexec_b64 s[4:5], s[8:9]
	s_cbranch_execz .LBB0_802
	v_lshl_add_u64 v[84:85], v[114:115], 2, s[14:15]
	s_waitcnt lgkmcnt(0)
	v_add_f32_e32 v82, v82, v83
	global_atomic_add_f32 v[84:85], v82, off
;     __device__ __forceinline__ void operator()(const f32x4 (&acc)[2][2][4][2], const Unit& u, int wr, int wc, int fr, int fq) const {
;     ...
; #pragma unroll
;         for (int g = 0; g < 8; ++g) {
;             const int ai = g >> 2, m = g & 3;
;             const int r = row0 + ai * HALF + m * 16; float ss = 0.f;
;             if (g < 7) { const int rn = row0 + ((g + 1) >> 2) * HALF + ((g + 1) & 3) * 16;
; #pragma unroll
;                 for (int bj = 0; bj < 2; ++bj)
; #pragma unroll
;                     for (int n = 0; n < 2; ++n) hnx[bj][n] = *(const h16x4*)(HB + (size_t)rn * D + col0 + bj * HALF + n * 16); }
; #pragma unroll
;             for (int bj = 0; bj < 2; ++bj)
; #pragma unroll
;                 for (int n = 0; n < 2; ++n) {
;                     const size_t o = (size_t)r * D + col0 + bj * HALF + n * 16;
;                     f32x4 hv; hv[0] = (float)hin[bj][n][0]; hv[1] = (float)hin[bj][n][1]; hv[2] = (float)hin[bj][n][2]; hv[3] = (float)hin[bj][n][3];
;                     hv += acc[ai][bj][m][n];
;                     ss += hv[0] * hv[0] + hv[1] * hv[1] + hv[2] * hv[2] + hv[3] * hv[3];
;                     if (OUT != nullptr) *(f32x4*)(OUT + o) = hv;
;                     else { h16x4 hh; hh[0] = (h16)hv[0]; hh[1] = (h16)hv[1]; hh[2] = (h16)hv[2]; hh[3] = (h16)hv[3]; *(h16x4*)(HB + o) = hh; }
;                 }
;             ss += __shfl_xor(ss, 16); ss += __shfl_xor(ss, 32);
;             if (fq == 0) atomicAdd(rsq_next + r, ss);
.LBB0_802:
	s_or_b64 exec, exec, s[4:5]
	v_add_u32_e32 v82, 0x80, v138
	s_waitcnt lgkmcnt(0)
	v_ashrrev_i32_e32 v83, 31, v82
	v_lshlrev_b64 v[84:85], 11, v[82:83]
	v_lshl_add_u64 v[84:85], s[12:13], 0, v[84:85]
	v_lshl_add_u64 v[84:85], v[136:137], 1, v[84:85]
	s_waitcnt vmcnt(27)
	v_mov_b32_e32 v92, v192
	v_mov_b32_e32 v93, v193
	v_mov_b32_e32 v90, v194
	v_mov_b32_e32 v91, v195
	v_mov_b32_e32 v88, v196
	v_mov_b32_e32 v89, v197
	v_mov_b32_e32 v86, v198
	v_mov_b32_e32 v87, v199
	s_nop 0
	v_cvt_f32_f16_sdwa v95, v108 dst_sel:DWORD dst_unused:UNUSED_PAD src0_sel:WORD_1
	v_cvt_f32_f16_e32 v94, v108
	v_cvt_f32_f16_sdwa v97, v109 dst_sel:DWORD dst_unused:UNUSED_PAD src0_sel:WORD_1
	v_cvt_f32_f16_e32 v96, v109
	v_pk_add_f32 v[78:79], v[78:79], v[94:95]
	s_nop 0
	v_mul_f32_e32 v108, v79, v79
	v_pk_add_f32 v[80:81], v[80:81], v[96:97]
	v_fmac_f32_e32 v108, v78, v78
	v_fmac_f32_e32 v108, v80, v80
	v_fmac_f32_e32 v108, v81, v81
	v_cvt_pk_f16_f32 v81, v80, v81
	s_nop 0
	v_cvt_f32_f16_sdwa v95, v106 dst_sel:DWORD dst_unused:UNUSED_PAD src0_sel:WORD_1
	v_cvt_f32_f16_e32 v94, v106
	v_cvt_pk_f16_f32 v80, v78, v79
	s_nop 0
	v_cvt_f32_f16_sdwa v79, v104 dst_sel:DWORD dst_unused:UNUSED_PAD src0_sel:WORD_1
	v_cvt_f32_f16_e32 v78, v104
	v_cvt_f32_f16_sdwa v97, v107 dst_sel:DWORD dst_unused:UNUSED_PAD src0_sel:WORD_1
	v_cvt_f32_f16_e32 v96, v107
	global_store_dwordx2 v[100:101], v[80:81], off
	v_cvt_f32_f16_sdwa v81, v105 dst_sel:DWORD dst_unused:UNUSED_PAD src0_sel:WORD_1
	v_cvt_f32_f16_e32 v80, v105
	v_pk_add_f32 v[74:75], v[74:75], v[94:95]
	v_pk_add_f32 v[70:71], v[70:71], v[78:79]
	s_nop 0
	v_cvt_f32_f16_sdwa v79, v102 dst_sel:DWORD dst_unused:UNUSED_PAD src0_sel:WORD_1
	v_cvt_f32_f16_e32 v78, v102
	v_mul_f32_e32 v94, v75, v75
	v_pk_add_f32 v[76:77], v[76:77], v[96:97]
	v_fmac_f32_e32 v94, v74, v74
	v_pk_add_f32 v[72:73], v[72:73], v[80:81]
	v_cvt_f32_f16_sdwa v81, v103 dst_sel:DWORD dst_unused:UNUSED_PAD src0_sel:WORD_1
	v_cvt_f32_f16_e32 v80, v103
	v_fmac_f32_e32 v94, v76, v76
	v_fmac_f32_e32 v94, v77, v77
	v_cvt_pk_f16_f32 v77, v76, v77
	v_mul_f32_e32 v76, v71, v71
	v_pk_add_f32 v[78:79], v[66:67], v[78:79]
	v_fmac_f32_e32 v76, v70, v70
	v_mul_f32_e32 v66, v79, v79
	v_fmac_f32_e32 v76, v72, v72
	v_pk_add_f32 v[68:69], v[68:69], v[80:81]
	v_fmac_f32_e32 v66, v78, v78
	v_add_f32_e32 v94, v108, v94
	v_fmac_f32_e32 v76, v73, v73
	v_fmac_f32_e32 v66, v68, v68
	v_add_f32_e32 v76, v94, v76
	v_fmac_f32_e32 v66, v69, v69
	v_add_f32_e32 v66, v76, v66
	ds_bpermute_b32 v67, v161, v66
	v_cvt_pk_f16_f32 v76, v74, v75
	v_cvt_pk_f16_f32 v73, v72, v73
	v_cvt_pk_f16_f32 v72, v70, v71
	v_cvt_pk_f16_f32 v69, v68, v69
	s_waitcnt lgkmcnt(0)
	v_add_f32_e32 v66, v66, v67
	ds_bpermute_b32 v67, v162, v66
	v_cvt_pk_f16_f32 v68, v78, v79
	global_store_dwordx2 v[100:101], v[76:77], off offset:32
	global_store_dwordx2 v[100:101], v[72:73], off offset:256
	global_store_dwordx2 v[100:101], v[68:69], off offset:288
	s_and_saveexec_b64 s[4:5], s[8:9]
	s_cbranch_execz .LBB0_804
	v_lshl_add_u64 v[68:69], v[98:99], 2, s[14:15]
	s_waitcnt lgkmcnt(0)
	v_add_f32_e32 v66, v66, v67
	global_atomic_add_f32 v[68:69], v66, off
.LBB0_804:
	s_or_b64 exec, exec, s[4:5]
	v_or_b32_e32 v66, 16, v82
	s_waitcnt lgkmcnt(0)
	v_ashrrev_i32_e32 v67, 31, v66
	v_lshlrev_b64 v[68:69], 11, v[66:67]
	v_lshl_add_u64 v[68:69], s[12:13], 0, v[68:69]
	v_lshl_add_u64 v[68:69], v[136:137], 1, v[68:69]
	s_waitcnt vmcnt(28)
	v_mov_b32_e32 v76, v200
	v_mov_b32_e32 v77, v201
	v_mov_b32_e32 v74, v202
	v_mov_b32_e32 v75, v203
	v_mov_b32_e32 v72, v204
	v_mov_b32_e32 v73, v205
	v_mov_b32_e32 v70, v206
	v_mov_b32_e32 v71, v207
	s_nop 0
	v_cvt_f32_f16_sdwa v79, v92 dst_sel:DWORD dst_unused:UNUSED_PAD src0_sel:WORD_1
	v_cvt_f32_f16_e32 v78, v92
	v_cvt_f32_f16_sdwa v81, v93 dst_sel:DWORD dst_unused:UNUSED_PAD src0_sel:WORD_1
	v_cvt_f32_f16_e32 v80, v93
	v_pk_add_f32 v[62:63], v[62:63], v[78:79]
	s_nop 0
	v_mul_f32_e32 v92, v63, v63
	v_pk_add_f32 v[64:65], v[64:65], v[80:81]
	v_fmac_f32_e32 v92, v62, v62
	v_fmac_f32_e32 v92, v64, v64
	v_fmac_f32_e32 v92, v65, v65
	v_cvt_pk_f16_f32 v65, v64, v65
	s_nop 0
	v_cvt_f32_f16_sdwa v79, v90 dst_sel:DWORD dst_unused:UNUSED_PAD src0_sel:WORD_1
	v_cvt_f32_f16_e32 v78, v90
	v_cvt_pk_f16_f32 v64, v62, v63
	s_nop 0
	v_cvt_f32_f16_sdwa v63, v88 dst_sel:DWORD dst_unused:UNUSED_PAD src0_sel:WORD_1
	v_cvt_f32_f16_e32 v62, v88
	v_cvt_f32_f16_sdwa v81, v91 dst_sel:DWORD dst_unused:UNUSED_PAD src0_sel:WORD_1
	v_cvt_f32_f16_e32 v80, v91
	global_store_dwordx2 v[84:85], v[64:65], off
	v_cvt_f32_f16_sdwa v65, v89 dst_sel:DWORD dst_unused:UNUSED_PAD src0_sel:WORD_1
	v_cvt_f32_f16_e32 v64, v89
	v_pk_add_f32 v[58:59], v[58:59], v[78:79]
	v_pk_add_f32 v[54:55], v[54:55], v[62:63]
	s_nop 0
	v_cvt_f32_f16_sdwa v63, v86 dst_sel:DWORD dst_unused:UNUSED_PAD src0_sel:WORD_1
	v_cvt_f32_f16_e32 v62, v86
	v_mul_f32_e32 v78, v59, v59
	v_pk_add_f32 v[60:61], v[60:61], v[80:81]
	v_fmac_f32_e32 v78, v58, v58
	v_pk_add_f32 v[56:57], v[56:57], v[64:65]
	v_cvt_f32_f16_sdwa v65, v87 dst_sel:DWORD dst_unused:UNUSED_PAD src0_sel:WORD_1
	v_cvt_f32_f16_e32 v64, v87
	v_fmac_f32_e32 v78, v60, v60
	v_fmac_f32_e32 v78, v61, v61
	v_cvt_pk_f16_f32 v61, v60, v61
	v_mul_f32_e32 v60, v55, v55
	v_pk_add_f32 v[62:63], v[50:51], v[62:63]
	v_fmac_f32_e32 v60, v54, v54
	v_mul_f32_e32 v50, v63, v63
	v_fmac_f32_e32 v60, v56, v56
	v_pk_add_f32 v[52:53], v[52:53], v[64:65]
	v_fmac_f32_e32 v50, v62, v62
	v_add_f32_e32 v78, v92, v78
	v_fmac_f32_e32 v60, v57, v57
	v_fmac_f32_e32 v50, v52, v52
	v_add_f32_e32 v60, v78, v60
	v_fmac_f32_e32 v50, v53, v53
	v_add_f32_e32 v50, v60, v50
	ds_bpermute_b32 v51, v161, v50
	v_cvt_pk_f16_f32 v60, v58, v59
	v_cvt_pk_f16_f32 v57, v56, v57
	v_cvt_pk_f16_f32 v56, v54, v55
	v_cvt_pk_f16_f32 v53, v52, v53
	s_waitcnt lgkmcnt(0)
	v_add_f32_e32 v50, v50, v51
	ds_bpermute_b32 v51, v162, v50
	v_cvt_pk_f16_f32 v52, v62, v63
	global_store_dwordx2 v[84:85], v[60:61], off offset:32
	global_store_dwordx2 v[84:85], v[56:57], off offset:256
	global_store_dwordx2 v[84:85], v[52:53], off offset:288
	s_and_saveexec_b64 s[4:5], s[8:9]
	s_cbranch_execz .LBB0_806
	v_lshl_add_u64 v[52:53], v[82:83], 2, s[14:15]
	s_waitcnt lgkmcnt(0)
	v_add_f32_e32 v50, v50, v51
	global_atomic_add_f32 v[52:53], v50, off
;     __device__ __forceinline__ void operator()(const f32x4 (&acc)[2][2][4][2], const Unit& u, int wr, int wc, int fr, int fq) const {
;     ...
; #pragma unroll
;         for (int g = 0; g < 8; ++g) {
;             const int ai = g >> 2, m = g & 3;
;             const int r = row0 + ai * HALF + m * 16; float ss = 0.f;
;             if (g < 7) { const int rn = row0 + ((g + 1) >> 2) * HALF + ((g + 1) & 3) * 16;
; #pragma unroll
;                 for (int bj = 0; bj < 2; ++bj)
; #pragma unroll
;                     for (int n = 0; n < 2; ++n) hnx[bj][n] = *(const h16x4*)(HB + (size_t)rn * D + col0 + bj * HALF + n * 16); }
; #pragma unroll
;             for (int bj = 0; bj < 2; ++bj)
; #pragma unroll
;                 for (int n = 0; n < 2; ++n) {
;                     const size_t o = (size_t)r * D + col0 + bj * HALF + n * 16;
;                     f32x4 hv; hv[0] = (float)hin[bj][n][0]; hv[1] = (float)hin[bj][n][1]; hv[2] = (float)hin[bj][n][2]; hv[3] = (float)hin[bj][n][3];
;                     hv += acc[ai][bj][m][n];
;                     ss += hv[0] * hv[0] + hv[1] * hv[1] + hv[2] * hv[2] + hv[3] * hv[3];
;                     if (OUT != nullptr) *(f32x4*)(OUT + o) = hv;
;                     else { h16x4 hh; hh[0] = (h16)hv[0]; hh[1] = (h16)hv[1]; hh[2] = (h16)hv[2]; hh[3] = (h16)hv[3]; *(h16x4*)(HB + o) = hh; }
;                 }
;             ss += __shfl_xor(ss, 16); ss += __shfl_xor(ss, 32);
;             if (fq == 0) atomicAdd(rsq_next + r, ss);
.LBB0_806:
	s_or_b64 exec, exec, s[4:5]
	v_or_b32_e32 v50, 32, v82
	s_waitcnt lgkmcnt(0)
	v_ashrrev_i32_e32 v51, 31, v50
	v_lshlrev_b64 v[52:53], 11, v[50:51]
	v_lshl_add_u64 v[52:53], s[12:13], 0, v[52:53]
	v_lshl_add_u64 v[52:53], v[136:137], 1, v[52:53]
	s_waitcnt vmcnt(29)
	v_mov_b32_e32 v60, v208
	v_mov_b32_e32 v61, v209
	v_mov_b32_e32 v58, v210
	v_mov_b32_e32 v59, v211
	v_mov_b32_e32 v56, v212
	v_mov_b32_e32 v57, v213
	v_mov_b32_e32 v54, v232
	v_mov_b32_e32 v55, v233
	s_nop 0
	v_cvt_f32_f16_sdwa v63, v76 dst_sel:DWORD dst_unused:UNUSED_PAD src0_sel:WORD_1
	v_cvt_f32_f16_e32 v62, v76
	v_cvt_f32_f16_sdwa v65, v77 dst_sel:DWORD dst_unused:UNUSED_PAD src0_sel:WORD_1
	v_cvt_f32_f16_e32 v64, v77
	v_pk_add_f32 v[46:47], v[46:47], v[62:63]
	s_nop 0
	v_mul_f32_e32 v76, v47, v47
	v_pk_add_f32 v[48:49], v[48:49], v[64:65]
	v_fmac_f32_e32 v76, v46, v46
	v_fmac_f32_e32 v76, v48, v48
	v_fmac_f32_e32 v76, v49, v49
	v_cvt_pk_f16_f32 v49, v48, v49
	s_nop 0
	v_cvt_f32_f16_sdwa v63, v74 dst_sel:DWORD dst_unused:UNUSED_PAD src0_sel:WORD_1
	v_cvt_f32_f16_e32 v62, v74
	v_cvt_pk_f16_f32 v48, v46, v47
	s_nop 0
	v_cvt_f32_f16_sdwa v47, v72 dst_sel:DWORD dst_unused:UNUSED_PAD src0_sel:WORD_1
	v_cvt_f32_f16_e32 v46, v72
	v_cvt_f32_f16_sdwa v65, v75 dst_sel:DWORD dst_unused:UNUSED_PAD src0_sel:WORD_1
	v_cvt_f32_f16_e32 v64, v75
	global_store_dwordx2 v[68:69], v[48:49], off
	v_cvt_f32_f16_sdwa v49, v73 dst_sel:DWORD dst_unused:UNUSED_PAD src0_sel:WORD_1
	v_cvt_f32_f16_e32 v48, v73
	v_pk_add_f32 v[42:43], v[42:43], v[62:63]
	v_pk_add_f32 v[38:39], v[38:39], v[46:47]
	s_nop 0
	v_cvt_f32_f16_sdwa v47, v70 dst_sel:DWORD dst_unused:UNUSED_PAD src0_sel:WORD_1
	v_cvt_f32_f16_e32 v46, v70
	v_mul_f32_e32 v62, v43, v43
	v_pk_add_f32 v[44:45], v[44:45], v[64:65]
	v_fmac_f32_e32 v62, v42, v42
	v_pk_add_f32 v[40:41], v[40:41], v[48:49]
	v_cvt_f32_f16_sdwa v49, v71 dst_sel:DWORD dst_unused:UNUSED_PAD src0_sel:WORD_1
	v_cvt_f32_f16_e32 v48, v71
	v_fmac_f32_e32 v62, v44, v44
	v_fmac_f32_e32 v62, v45, v45
	v_cvt_pk_f16_f32 v45, v44, v45
	v_mul_f32_e32 v44, v39, v39
	v_pk_add_f32 v[46:47], v[34:35], v[46:47]
	v_fmac_f32_e32 v44, v38, v38
	v_mul_f32_e32 v34, v47, v47
	v_fmac_f32_e32 v44, v40, v40
	v_pk_add_f32 v[36:37], v[36:37], v[48:49]
	v_fmac_f32_e32 v34, v46, v46
	v_add_f32_e32 v62, v76, v62
	v_fmac_f32_e32 v44, v41, v41
	v_fmac_f32_e32 v34, v36, v36
	v_add_f32_e32 v44, v62, v44
	v_fmac_f32_e32 v34, v37, v37
	v_add_f32_e32 v34, v44, v34
	ds_bpermute_b32 v35, v161, v34
	v_cvt_pk_f16_f32 v44, v42, v43
	v_cvt_pk_f16_f32 v41, v40, v41
	v_cvt_pk_f16_f32 v40, v38, v39
	v_cvt_pk_f16_f32 v37, v36, v37
	s_waitcnt lgkmcnt(0)
	v_add_f32_e32 v34, v34, v35
	ds_bpermute_b32 v35, v162, v34
	v_cvt_pk_f16_f32 v36, v46, v47
	global_store_dwordx2 v[68:69], v[44:45], off offset:32
	global_store_dwordx2 v[68:69], v[40:41], off offset:256
	global_store_dwordx2 v[68:69], v[36:37], off offset:288
	s_and_saveexec_b64 s[4:5], s[8:9]
	s_cbranch_execz .LBB0_808
	v_lshl_add_u64 v[36:37], v[66:67], 2, s[14:15]
	s_waitcnt lgkmcnt(0)
	v_add_f32_e32 v34, v34, v35
	global_atomic_add_f32 v[36:37], v34, off
;     __device__ __forceinline__ void operator()(const f32x4 (&acc)[2][2][4][2], const Unit& u, int wr, int wc, int fr, int fq) const {
;     ...
; #pragma unroll
;         for (int g = 0; g < 8; ++g) {
;             const int ai = g >> 2, m = g & 3;
;             const int r = row0 + ai * HALF + m * 16; float ss = 0.f;
;             if (g < 7) { const int rn = row0 + ((g + 1) >> 2) * HALF + ((g + 1) & 3) * 16;
; #pragma unroll
;                 for (int bj = 0; bj < 2; ++bj)
; #pragma unroll
;                     for (int n = 0; n < 2; ++n) hnx[bj][n] = *(const h16x4*)(HB + (size_t)rn * D + col0 + bj * HALF + n * 16); }
; #pragma unroll
;             for (int bj = 0; bj < 2; ++bj)
; #pragma unroll
;                 for (int n = 0; n < 2; ++n) {
;                     const size_t o = (size_t)r * D + col0 + bj * HALF + n * 16;
;                     f32x4 hv; hv[0] = (float)hin[bj][n][0]; hv[1] = (float)hin[bj][n][1]; hv[2] = (float)hin[bj][n][2]; hv[3] = (float)hin[bj][n][3];
;                     hv += acc[ai][bj][m][n];
;                     ss += hv[0] * hv[0] + hv[1] * hv[1] + hv[2] * hv[2] + hv[3] * hv[3];
;                     if (OUT != nullptr) *(f32x4*)(OUT + o) = hv;
;                     else { h16x4 hh; hh[0] = (h16)hv[0]; hh[1] = (h16)hv[1]; hh[2] = (h16)hv[2]; hh[3] = (h16)hv[3]; *(h16x4*)(HB + o) = hh; }
;                 }
;             ss += __shfl_xor(ss, 16); ss += __shfl_xor(ss, 32);
;             if (fq == 0) atomicAdd(rsq_next + r, ss);
.LBB0_808:
	s_or_b64 exec, exec, s[4:5]
	v_or_b32_e32 v34, 48, v82
	s_waitcnt lgkmcnt(0)
	v_ashrrev_i32_e32 v35, 31, v34
	v_lshlrev_b64 v[36:37], 11, v[34:35]
	v_lshl_add_u64 v[36:37], s[12:13], 0, v[36:37]
	v_lshl_add_u64 v[36:37], v[136:137], 1, v[36:37]
	s_waitcnt vmcnt(30)
	v_mov_b32_e32 v44, v234
	v_mov_b32_e32 v45, v235
	v_mov_b32_e32 v42, v236
	v_mov_b32_e32 v43, v237
	v_mov_b32_e32 v40, v238
	v_mov_b32_e32 v41, v239
	v_mov_b32_e32 v38, v240
	v_mov_b32_e32 v39, v241
	s_nop 0
	v_cvt_f32_f16_sdwa v47, v60 dst_sel:DWORD dst_unused:UNUSED_PAD src0_sel:WORD_1
	v_cvt_f32_f16_e32 v46, v60
	v_cvt_f32_f16_sdwa v49, v61 dst_sel:DWORD dst_unused:UNUSED_PAD src0_sel:WORD_1
	v_cvt_f32_f16_e32 v48, v61
	v_pk_add_f32 v[30:31], v[30:31], v[46:47]
	s_nop 0
	v_mul_f32_e32 v60, v31, v31
	v_pk_add_f32 v[32:33], v[32:33], v[48:49]
	v_fmac_f32_e32 v60, v30, v30
	v_fmac_f32_e32 v60, v32, v32
	v_fmac_f32_e32 v60, v33, v33
	v_cvt_pk_f16_f32 v33, v32, v33
	s_nop 0
	v_cvt_f32_f16_sdwa v47, v58 dst_sel:DWORD dst_unused:UNUSED_PAD src0_sel:WORD_1
	v_cvt_f32_f16_e32 v46, v58
	v_cvt_pk_f16_f32 v32, v30, v31
	s_nop 0
	v_cvt_f32_f16_sdwa v31, v56 dst_sel:DWORD dst_unused:UNUSED_PAD src0_sel:WORD_1
	v_cvt_f32_f16_e32 v30, v56
	v_cvt_f32_f16_sdwa v49, v59 dst_sel:DWORD dst_unused:UNUSED_PAD src0_sel:WORD_1
	v_cvt_f32_f16_e32 v48, v59
	global_store_dwordx2 v[52:53], v[32:33], off
	v_cvt_f32_f16_sdwa v33, v57 dst_sel:DWORD dst_unused:UNUSED_PAD src0_sel:WORD_1
	v_cvt_f32_f16_e32 v32, v57
	v_pk_add_f32 v[26:27], v[26:27], v[46:47]
	v_pk_add_f32 v[22:23], v[22:23], v[30:31]
	s_nop 0
	v_cvt_f32_f16_sdwa v31, v54 dst_sel:DWORD dst_unused:UNUSED_PAD src0_sel:WORD_1
	v_cvt_f32_f16_e32 v30, v54
	v_mul_f32_e32 v46, v27, v27
	v_pk_add_f32 v[28:29], v[28:29], v[48:49]
	v_fmac_f32_e32 v46, v26, v26
	v_pk_add_f32 v[24:25], v[24:25], v[32:33]
	v_cvt_f32_f16_sdwa v33, v55 dst_sel:DWORD dst_unused:UNUSED_PAD src0_sel:WORD_1
	v_cvt_f32_f16_e32 v32, v55
	v_fmac_f32_e32 v46, v28, v28
	v_fmac_f32_e32 v46, v29, v29
	v_cvt_pk_f16_f32 v29, v28, v29
	v_mul_f32_e32 v28, v23, v23
	v_pk_add_f32 v[30:31], v[18:19], v[30:31]
	v_fmac_f32_e32 v28, v22, v22
	v_mul_f32_e32 v18, v31, v31
	v_fmac_f32_e32 v28, v24, v24
	v_pk_add_f32 v[20:21], v[20:21], v[32:33]
	v_fmac_f32_e32 v18, v30, v30
	v_add_f32_e32 v46, v60, v46
	v_fmac_f32_e32 v28, v25, v25
	v_fmac_f32_e32 v18, v20, v20
	v_add_f32_e32 v28, v46, v28
	v_fmac_f32_e32 v18, v21, v21
	v_add_f32_e32 v18, v28, v18
	ds_bpermute_b32 v19, v161, v18
	v_cvt_pk_f16_f32 v28, v26, v27
	v_cvt_pk_f16_f32 v25, v24, v25
	v_cvt_pk_f16_f32 v24, v22, v23
	v_cvt_pk_f16_f32 v21, v20, v21
	s_waitcnt lgkmcnt(0)
	v_add_f32_e32 v18, v18, v19
	ds_bpermute_b32 v19, v162, v18
	v_cvt_pk_f16_f32 v20, v30, v31
	global_store_dwordx2 v[52:53], v[28:29], off offset:32
	global_store_dwordx2 v[52:53], v[24:25], off offset:256
	global_store_dwordx2 v[52:53], v[20:21], off offset:288
	s_and_saveexec_b64 s[4:5], s[8:9]
	s_cbranch_execz .LBB0_810
	v_lshl_add_u64 v[20:21], v[50:51], 2, s[14:15]
	s_waitcnt lgkmcnt(0)
	v_add_f32_e32 v18, v18, v19
	global_atomic_add_f32 v[20:21], v18, off
.LBB0_810:
	s_or_b64 exec, exec, s[4:5]
	s_waitcnt lgkmcnt(0)
	v_cvt_f32_f16_sdwa v19, v44 dst_sel:DWORD dst_unused:UNUSED_PAD src0_sel:WORD_1
	v_cvt_f32_f16_e32 v18, v44
	v_cvt_f32_f16_sdwa v21, v45 dst_sel:DWORD dst_unused:UNUSED_PAD src0_sel:WORD_1
	v_cvt_f32_f16_e32 v20, v45
	v_pk_add_f32 v[14:15], v[14:15], v[18:19]
	s_nop 0
	v_mul_f32_e32 v22, v15, v15
	v_pk_add_f32 v[16:17], v[16:17], v[20:21]
	v_fmac_f32_e32 v22, v14, v14
	v_fmac_f32_e32 v22, v16, v16
	v_fmac_f32_e32 v22, v17, v17
	v_cvt_pk_f16_f32 v17, v16, v17
	s_nop 0
	v_cvt_f32_f16_sdwa v19, v42 dst_sel:DWORD dst_unused:UNUSED_PAD src0_sel:WORD_1
	v_cvt_f32_f16_e32 v18, v42
	v_cvt_pk_f16_f32 v16, v14, v15
	s_nop 0
	v_cvt_f32_f16_sdwa v15, v40 dst_sel:DWORD dst_unused:UNUSED_PAD src0_sel:WORD_1
	v_cvt_f32_f16_e32 v14, v40
	v_cvt_f32_f16_sdwa v21, v43 dst_sel:DWORD dst_unused:UNUSED_PAD src0_sel:WORD_1
	v_cvt_f32_f16_e32 v20, v43
	global_store_dwordx2 v[36:37], v[16:17], off
	v_cvt_f32_f16_sdwa v17, v41 dst_sel:DWORD dst_unused:UNUSED_PAD src0_sel:WORD_1
	v_cvt_f32_f16_e32 v16, v41
	v_pk_add_f32 v[10:11], v[10:11], v[18:19]
	v_pk_add_f32 v[6:7], v[6:7], v[14:15]
	s_nop 0
	v_cvt_f32_f16_sdwa v15, v38 dst_sel:DWORD dst_unused:UNUSED_PAD src0_sel:WORD_1
	v_cvt_f32_f16_e32 v14, v38
	v_mul_f32_e32 v18, v11, v11
	v_pk_add_f32 v[12:13], v[12:13], v[20:21]
	v_fmac_f32_e32 v18, v10, v10
	v_pk_add_f32 v[8:9], v[8:9], v[16:17]
	v_cvt_f32_f16_sdwa v17, v39 dst_sel:DWORD dst_unused:UNUSED_PAD src0_sel:WORD_1
	v_cvt_f32_f16_e32 v16, v39
	v_fmac_f32_e32 v18, v12, v12
	v_fmac_f32_e32 v18, v13, v13
	v_cvt_pk_f16_f32 v13, v12, v13
	v_mul_f32_e32 v12, v7, v7
	v_pk_add_f32 v[14:15], v[2:3], v[14:15]
	v_fmac_f32_e32 v12, v6, v6
	v_mul_f32_e32 v2, v15, v15
	v_fmac_f32_e32 v12, v8, v8
	v_pk_add_f32 v[4:5], v[4:5], v[16:17]
	v_fmac_f32_e32 v2, v14, v14
	v_add_f32_e32 v18, v22, v18
	v_fmac_f32_e32 v12, v9, v9
	v_fmac_f32_e32 v2, v4, v4
	v_add_f32_e32 v12, v18, v12
	v_fmac_f32_e32 v2, v5, v5
	v_add_f32_e32 v2, v12, v2
	ds_bpermute_b32 v3, v161, v2
	v_cvt_pk_f16_f32 v12, v10, v11
	v_cvt_pk_f16_f32 v9, v8, v9
	v_cvt_pk_f16_f32 v8, v6, v7
	v_cvt_pk_f16_f32 v5, v4, v5
	s_waitcnt lgkmcnt(0)
	v_add_f32_e32 v2, v2, v3
	ds_bpermute_b32 v3, v162, v2
	v_cvt_pk_f16_f32 v4, v14, v15
	global_store_dwordx2 v[36:37], v[12:13], off offset:32
	global_store_dwordx2 v[36:37], v[8:9], off offset:256
	global_store_dwordx2 v[36:37], v[4:5], off offset:288
	s_and_saveexec_b64 s[4:5], s[8:9]
	s_cbranch_execz .LBB0_787
	v_lshl_add_u64 v[4:5], v[34:35], 2, s[14:15]
	s_waitcnt lgkmcnt(0)
	v_add_f32_e32 v2, v2, v3
	global_atomic_add_f32 v[4:5], v2, off
	s_branch .LBB0_787

;     __device__ __forceinline__ void operator()(const f32x4 (&acc)[2][2][4][2], const Unit& u, int wr, int wc, int fr, int fq) const {
;         const int row0 = u.pm * BM + wr * 64 + fr, col0 = u.pn * BM + wc * 32 + 4 * fq;
;         h16x4 hin[2][2], hnx[2][2];
; #pragma unroll
;         for (int bj = 0; bj < 2; ++bj)
; #pragma unroll
;             for (int n = 0; n < 2; ++n) hin[bj][n] = *(const h16x4*)(HB + (size_t)row0 * D + col0 + bj * HALF + n * 16);
; #pragma unroll
;         for (int g = 0; g < 8; ++g) {
;             const int ai = g >> 2, m = g & 3;
;             const int r = row0 + ai * HALF + m * 16; float ss = 0.f;
;             if (g < 7) { const int rn = row0 + ((g + 1) >> 2) * HALF + ((g + 1) & 3) * 16;
; #pragma unroll
;                 for (int bj = 0; bj < 2; ++bj)
; #pragma unroll
;                     for (int n = 0; n < 2; ++n) hnx[bj][n] = *(const h16x4*)(HB + (size_t)rn * D + col0 + bj * HALF + n * 16); }
; #pragma unroll
;             for (int bj = 0; bj < 2; ++bj)
; #pragma unroll
;                 for (int n = 0; n < 2; ++n) {
;                     const size_t o = (size_t)r * D + col0 + bj * HALF + n * 16;
;                     f32x4 hv; hv[0] = (float)hin[bj][n][0]; hv[1] = (float)hin[bj][n][1]; hv[2] = (float)hin[bj][n][2]; hv[3] = (float)hin[bj][n][3];
;                     hv += acc[ai][bj][m][n];
;                     ss += hv[0] * hv[0] + hv[1] * hv[1] + hv[2] * hv[2] + hv[3] * hv[3];
;                     if (OUT != nullptr) *(f32x4*)(OUT + o) = hv;
;                     else { h16x4 hh; hh[0] = (h16)hv[0]; hh[1] = (h16)hv[1]; hh[2] = (h16)hv[2]; hh[3] = (h16)hv[3]; *(h16x4*)(HB + o) = hh; }
;                 }
;             ss += __shfl_xor(ss, 16); ss += __shfl_xor(ss, 32);
;             if (fq == 0) atomicAdd(rsq_next + r, ss);
.Lalign_evout_a:
	v_lshl_add_u32 v138, s43, 8, v154
	v_lshl_or_b32 v136, s42, 8, v163
	v_ashrrev_i32_e32 v139, 31, v138
	v_lshlrev_b64 v[140:141], 11, v[138:139]
	v_ashrrev_i32_e32 v137, 31, v136
	v_lshl_add_u64 v[140:141], s[10:11], 0, v[140:141]
	v_lshlrev_b64 v[142:143], 1, v[136:137]
	v_lshl_add_u64 v[152:153], v[140:141], 0, v[142:143]
	global_load_dwordx2 v[166:167], v[152:153], off
	global_load_dwordx2 v[168:169], v[152:153], off offset:32
	global_load_dwordx2 v[170:171], v[152:153], off offset:256
	global_load_dwordx2 v[172:173], v[152:153], off offset:288
	v_or_b32_e32 v140, 16, v138
	v_ashrrev_i32_e32 v141, 31, v140
	v_lshlrev_b64 v[144:145], 11, v[140:141]
	v_lshl_add_u64 v[144:145], s[10:11], 0, v[144:145]
	v_lshl_add_u64 v[142:143], v[144:145], 0, v[142:143]
	global_load_dwordx2 v[150:151], v[142:143], off
	global_load_dwordx2 v[148:149], v[142:143], off offset:32
	global_load_dwordx2 v[146:147], v[142:143], off offset:256
	global_load_dwordx2 v[144:145], v[142:143], off offset:288
	v_lshlrev_b32_e32 v242, 11, v138
	v_lshl_add_u32 v242, v136, 1, v242
	v_add_u32_e32 v243, 0x10000, v242
	global_load_dwordx2 v[176:177], v243, s[10:11]
	global_load_dwordx2 v[178:179], v243, s[10:11] offset:32
	global_load_dwordx2 v[180:181], v243, s[10:11] offset:256
	global_load_dwordx2 v[182:183], v243, s[10:11] offset:288
	v_add_u32_e32 v243, 0x18000, v242
	global_load_dwordx2 v[184:185], v243, s[10:11]
	global_load_dwordx2 v[186:187], v243, s[10:11] offset:32
	global_load_dwordx2 v[188:189], v243, s[10:11] offset:256
	global_load_dwordx2 v[190:191], v243, s[10:11] offset:288
	v_add_u32_e32 v243, 0x40000, v242
	global_load_dwordx2 v[192:193], v243, s[10:11]
	global_load_dwordx2 v[194:195], v243, s[10:11] offset:32
	global_load_dwordx2 v[196:197], v243, s[10:11] offset:256
	global_load_dwordx2 v[198:199], v243, s[10:11] offset:288
	v_add_u32_e32 v243, 0x48000, v242
	global_load_dwordx2 v[200:201], v243, s[10:11]
	global_load_dwordx2 v[202:203], v243, s[10:11] offset:32
	global_load_dwordx2 v[204:205], v243, s[10:11] offset:256
	global_load_dwordx2 v[206:207], v243, s[10:11] offset:288
	v_add_u32_e32 v243, 0x50000, v242
	global_load_dwordx2 v[208:209], v243, s[10:11]
	global_load_dwordx2 v[210:211], v243, s[10:11] offset:32
	global_load_dwordx2 v[212:213], v243, s[10:11] offset:256
	global_load_dwordx2 v[232:233], v243, s[10:11] offset:288
	v_add_u32_e32 v243, 0x58000, v242
	global_load_dwordx2 v[234:235], v243, s[10:11]
	global_load_dwordx2 v[236:237], v243, s[10:11] offset:32
	global_load_dwordx2 v[238:239], v243, s[10:11] offset:256
	global_load_dwordx2 v[240:241], v243, s[10:11] offset:288
	s_waitcnt vmcnt(24)
	v_cvt_f32_f16_e32 v174, v166
	v_cvt_f32_f16_sdwa v175, v166 dst_sel:DWORD dst_unused:UNUSED_PAD src0_sel:WORD_1
	v_cvt_f32_f16_e32 v166, v167
	v_cvt_f32_f16_sdwa v167, v167 dst_sel:DWORD dst_unused:UNUSED_PAD src0_sel:WORD_1
	v_pk_add_f32 v[126:127], v[126:127], v[174:175]
	s_nop 0
	v_mul_f32_e32 v165, v127, v127
	v_pk_add_f32 v[128:129], v[128:129], v[166:167]
	v_fmac_f32_e32 v165, v126, v126
	v_fmac_f32_e32 v165, v128, v128
	v_fmac_f32_e32 v165, v129, v129
	v_cvt_pk_f16_f32 v129, v128, v129
	v_cvt_pk_f16_f32 v128, v126, v127
	v_cvt_f32_f16_e32 v126, v168
	v_cvt_f32_f16_sdwa v127, v168 dst_sel:DWORD dst_unused:UNUSED_PAD src0_sel:WORD_1
	global_store_dwordx2 v[152:153], v[128:129], off
	v_cvt_f32_f16_e32 v128, v169
	v_cvt_f32_f16_sdwa v129, v169 dst_sel:DWORD dst_unused:UNUSED_PAD src0_sel:WORD_1
	v_pk_add_f32 v[122:123], v[122:123], v[126:127]
	v_pk_add_f32 v[124:125], v[124:125], v[128:129]
	v_mul_f32_e32 v126, v123, v123
	v_fmac_f32_e32 v126, v122, v122
	v_fmac_f32_e32 v126, v124, v124
	v_fmac_f32_e32 v126, v125, v125
	v_cvt_pk_f16_f32 v125, v124, v125
	v_cvt_pk_f16_f32 v124, v122, v123
	v_cvt_f32_f16_e32 v122, v170
	v_cvt_f32_f16_sdwa v123, v170 dst_sel:DWORD dst_unused:UNUSED_PAD src0_sel:WORD_1
	global_store_dwordx2 v[152:153], v[124:125], off offset:32
	v_cvt_f32_f16_e32 v124, v171
	v_cvt_f32_f16_sdwa v125, v171 dst_sel:DWORD dst_unused:UNUSED_PAD src0_sel:WORD_1
	v_pk_add_f32 v[118:119], v[118:119], v[122:123]
	v_add_f32_e32 v126, v165, v126
	v_mul_f32_e32 v122, v119, v119
	v_pk_add_f32 v[120:121], v[120:121], v[124:125]
	v_fmac_f32_e32 v122, v118, v118
	v_fmac_f32_e32 v122, v120, v120
	v_fmac_f32_e32 v122, v121, v121
	v_cvt_pk_f16_f32 v121, v120, v121
	v_cvt_pk_f16_f32 v120, v118, v119
	v_cvt_f32_f16_e32 v118, v172
	v_cvt_f32_f16_sdwa v119, v172 dst_sel:DWORD dst_unused:UNUSED_PAD src0_sel:WORD_1
	global_store_dwordx2 v[152:153], v[120:121], off offset:256
	v_cvt_f32_f16_e32 v120, v173
	v_cvt_f32_f16_sdwa v121, v173 dst_sel:DWORD dst_unused:UNUSED_PAD src0_sel:WORD_1
	v_pk_add_f32 v[114:115], v[114:115], v[118:119]
	v_add_f32_e32 v122, v126, v122
	v_mul_f32_e32 v118, v115, v115
	v_pk_add_f32 v[116:117], v[116:117], v[120:121]
	v_fmac_f32_e32 v118, v114, v114
	v_fmac_f32_e32 v118, v116, v116
	v_fmac_f32_e32 v118, v117, v117
	v_add_f32_e32 v118, v122, v118
	v_cvt_pk_f16_f32 v117, v116, v117
	v_cvt_pk_f16_f32 v116, v114, v115
	ds_bpermute_b32 v114, v161, v118
	global_store_dwordx2 v[152:153], v[116:117], off offset:288
	s_waitcnt lgkmcnt(0)
	v_add_f32_e32 v114, v118, v114
	ds_bpermute_b32 v115, v162, v114
	s_and_saveexec_b64 s[4:5], s[6:7]
	s_cbranch_execz .LBB0_1375
	v_lshl_add_u64 v[116:117], v[138:139], 2, s[12:13]
	s_waitcnt lgkmcnt(0)
	v_add_f32_e32 v114, v114, v115
	global_atomic_add_f32 v[116:117], v114, off
;     __device__ __forceinline__ void operator()(const f32x4 (&acc)[2][2][4][2], const Unit& u, int wr, int wc, int fr, int fq) const {
;     ...
; #pragma unroll
;         for (int g = 0; g < 8; ++g) {
;             const int ai = g >> 2, m = g & 3;
;             const int r = row0 + ai * HALF + m * 16; float ss = 0.f;
;             if (g < 7) { const int rn = row0 + ((g + 1) >> 2) * HALF + ((g + 1) & 3) * 16;
; #pragma unroll
;                 for (int bj = 0; bj < 2; ++bj)
; #pragma unroll
;                     for (int n = 0; n < 2; ++n) hnx[bj][n] = *(const h16x4*)(HB + (size_t)rn * D + col0 + bj * HALF + n * 16); }
; #pragma unroll
;             for (int bj = 0; bj < 2; ++bj)
; #pragma unroll
;                 for (int n = 0; n < 2; ++n) {
;                     const size_t o = (size_t)r * D + col0 + bj * HALF + n * 16;
;                     f32x4 hv; hv[0] = (float)hin[bj][n][0]; hv[1] = (float)hin[bj][n][1]; hv[2] = (float)hin[bj][n][2]; hv[3] = (float)hin[bj][n][3];
;                     hv += acc[ai][bj][m][n];
;                     ss += hv[0] * hv[0] + hv[1] * hv[1] + hv[2] * hv[2] + hv[3] * hv[3];
;                     if (OUT != nullptr) *(f32x4*)(OUT + o) = hv;
;                     else { h16x4 hh; hh[0] = (h16)hv[0]; hh[1] = (h16)hv[1]; hh[2] = (h16)hv[2]; hh[3] = (h16)hv[3]; *(h16x4*)(HB + o) = hh; }
;                 }
;             ss += __shfl_xor(ss, 16); ss += __shfl_xor(ss, 32);
;             if (fq == 0) atomicAdd(rsq_next + r, ss);
.LBB0_1375:
	s_or_b64 exec, exec, s[4:5]
	v_or_b32_e32 v114, 32, v138
	s_waitcnt lgkmcnt(0)
	v_ashrrev_i32_e32 v115, 31, v114
	v_lshlrev_b64 v[116:117], 11, v[114:115]
	v_lshl_add_u64 v[116:117], s[10:11], 0, v[116:117]
	v_lshl_add_u64 v[116:117], v[136:137], 1, v[116:117]
	s_waitcnt vmcnt(25)
	v_mov_b32_e32 v124, v176
	v_mov_b32_e32 v125, v177
	v_mov_b32_e32 v122, v178
	v_mov_b32_e32 v123, v179
	v_mov_b32_e32 v120, v180
	v_mov_b32_e32 v121, v181
	v_mov_b32_e32 v118, v182
	v_mov_b32_e32 v119, v183
	v_cvt_f32_f16_sdwa v127, v150 dst_sel:DWORD dst_unused:UNUSED_PAD src0_sel:WORD_1
	v_cvt_f32_f16_e32 v126, v150
	v_cvt_f32_f16_sdwa v129, v151 dst_sel:DWORD dst_unused:UNUSED_PAD src0_sel:WORD_1
	v_cvt_f32_f16_e32 v128, v151
	v_pk_add_f32 v[110:111], v[110:111], v[126:127]
	s_nop 0
	v_mul_f32_e32 v139, v111, v111
	v_pk_add_f32 v[112:113], v[112:113], v[128:129]
	v_fmac_f32_e32 v139, v110, v110
	v_fmac_f32_e32 v139, v112, v112
	v_fmac_f32_e32 v139, v113, v113
	v_cvt_pk_f16_f32 v113, v112, v113
	v_cvt_f32_f16_sdwa v127, v148 dst_sel:DWORD dst_unused:UNUSED_PAD src0_sel:WORD_1
	v_cvt_f32_f16_e32 v126, v148
	v_cvt_pk_f16_f32 v112, v110, v111
	v_cvt_f32_f16_sdwa v111, v146 dst_sel:DWORD dst_unused:UNUSED_PAD src0_sel:WORD_1
	v_cvt_f32_f16_e32 v110, v146
	v_cvt_f32_f16_sdwa v129, v149 dst_sel:DWORD dst_unused:UNUSED_PAD src0_sel:WORD_1
	v_cvt_f32_f16_e32 v128, v149
	global_store_dwordx2 v[142:143], v[112:113], off
	v_cvt_f32_f16_sdwa v113, v147 dst_sel:DWORD dst_unused:UNUSED_PAD src0_sel:WORD_1
	v_cvt_f32_f16_e32 v112, v147
	v_pk_add_f32 v[106:107], v[106:107], v[126:127]
	v_pk_add_f32 v[102:103], v[102:103], v[110:111]
	v_cvt_f32_f16_sdwa v111, v144 dst_sel:DWORD dst_unused:UNUSED_PAD src0_sel:WORD_1
	v_cvt_f32_f16_e32 v110, v144
	v_mul_f32_e32 v126, v107, v107
	v_pk_add_f32 v[108:109], v[108:109], v[128:129]
	v_fmac_f32_e32 v126, v106, v106
	v_pk_add_f32 v[104:105], v[104:105], v[112:113]
	v_cvt_f32_f16_sdwa v113, v145 dst_sel:DWORD dst_unused:UNUSED_PAD src0_sel:WORD_1
	v_cvt_f32_f16_e32 v112, v145
	v_fmac_f32_e32 v126, v108, v108
	v_fmac_f32_e32 v126, v109, v109
	v_cvt_pk_f16_f32 v109, v108, v109
	v_mul_f32_e32 v108, v103, v103
	v_pk_add_f32 v[110:111], v[98:99], v[110:111]
	v_fmac_f32_e32 v108, v102, v102
	v_mul_f32_e32 v98, v111, v111
	v_fmac_f32_e32 v108, v104, v104
	v_pk_add_f32 v[100:101], v[100:101], v[112:113]
	v_fmac_f32_e32 v98, v110, v110
	v_add_f32_e32 v126, v139, v126
	v_fmac_f32_e32 v108, v105, v105
	v_fmac_f32_e32 v98, v100, v100
	v_add_f32_e32 v108, v126, v108
	v_fmac_f32_e32 v98, v101, v101
	v_add_f32_e32 v98, v108, v98
	ds_bpermute_b32 v99, v161, v98
	v_cvt_pk_f16_f32 v108, v106, v107
	v_cvt_pk_f16_f32 v105, v104, v105
	v_cvt_pk_f16_f32 v104, v102, v103
	v_cvt_pk_f16_f32 v101, v100, v101
	s_waitcnt lgkmcnt(0)
	v_add_f32_e32 v98, v98, v99
	ds_bpermute_b32 v99, v162, v98
	v_cvt_pk_f16_f32 v100, v110, v111
	global_store_dwordx2 v[142:143], v[108:109], off offset:32
	global_store_dwordx2 v[142:143], v[104:105], off offset:256
	global_store_dwordx2 v[142:143], v[100:101], off offset:288
	s_and_saveexec_b64 s[4:5], s[6:7]
	s_cbranch_execz .LBB0_1377
	v_lshl_add_u64 v[100:101], v[140:141], 2, s[12:13]
	s_waitcnt lgkmcnt(0)
	v_add_f32_e32 v98, v98, v99
	global_atomic_add_f32 v[100:101], v98, off
.LBB0_1377:
	s_or_b64 exec, exec, s[4:5]
	v_or_b32_e32 v98, 48, v138
	s_waitcnt lgkmcnt(0)
	v_ashrrev_i32_e32 v99, 31, v98
	v_lshlrev_b64 v[100:101], 11, v[98:99]
	v_lshl_add_u64 v[100:101], s[10:11], 0, v[100:101]
	v_lshl_add_u64 v[100:101], v[136:137], 1, v[100:101]
	s_waitcnt vmcnt(26)
	v_mov_b32_e32 v108, v184
	v_mov_b32_e32 v109, v185
	v_mov_b32_e32 v106, v186
	v_mov_b32_e32 v107, v187
	v_mov_b32_e32 v104, v188
	v_mov_b32_e32 v105, v189
	v_mov_b32_e32 v102, v190
	v_mov_b32_e32 v103, v191
	s_nop 0
	v_cvt_f32_f16_sdwa v111, v124 dst_sel:DWORD dst_unused:UNUSED_PAD src0_sel:WORD_1
	v_cvt_f32_f16_e32 v110, v124
	v_cvt_f32_f16_sdwa v113, v125 dst_sel:DWORD dst_unused:UNUSED_PAD src0_sel:WORD_1
	v_cvt_f32_f16_e32 v112, v125
	v_pk_add_f32 v[94:95], v[94:95], v[110:111]
	s_nop 0
	v_mul_f32_e32 v124, v95, v95
	v_pk_add_f32 v[96:97], v[96:97], v[112:113]
	v_fmac_f32_e32 v124, v94, v94
	v_fmac_f32_e32 v124, v96, v96
	v_fmac_f32_e32 v124, v97, v97
	v_cvt_pk_f16_f32 v97, v96, v97
	s_nop 0
	v_cvt_f32_f16_sdwa v111, v122 dst_sel:DWORD dst_unused:UNUSED_PAD src0_sel:WORD_1
	v_cvt_f32_f16_e32 v110, v122
	v_cvt_pk_f16_f32 v96, v94, v95
	s_nop 0
	v_cvt_f32_f16_sdwa v95, v120 dst_sel:DWORD dst_unused:UNUSED_PAD src0_sel:WORD_1
	v_cvt_f32_f16_e32 v94, v120
	v_cvt_f32_f16_sdwa v113, v123 dst_sel:DWORD dst_unused:UNUSED_PAD src0_sel:WORD_1
	v_cvt_f32_f16_e32 v112, v123
	global_store_dwordx2 v[116:117], v[96:97], off
	v_cvt_f32_f16_sdwa v97, v121 dst_sel:DWORD dst_unused:UNUSED_PAD src0_sel:WORD_1
	v_cvt_f32_f16_e32 v96, v121
	v_pk_add_f32 v[90:91], v[90:91], v[110:111]
	v_pk_add_f32 v[86:87], v[86:87], v[94:95]
	s_nop 0
	v_cvt_f32_f16_sdwa v95, v118 dst_sel:DWORD dst_unused:UNUSED_PAD src0_sel:WORD_1
	v_cvt_f32_f16_e32 v94, v118
	v_mul_f32_e32 v110, v91, v91
	v_pk_add_f32 v[92:93], v[92:93], v[112:113]
	v_fmac_f32_e32 v110, v90, v90
	v_pk_add_f32 v[88:89], v[88:89], v[96:97]
	v_cvt_f32_f16_sdwa v97, v119 dst_sel:DWORD dst_unused:UNUSED_PAD src0_sel:WORD_1
	v_cvt_f32_f16_e32 v96, v119
	v_fmac_f32_e32 v110, v92, v92
	v_fmac_f32_e32 v110, v93, v93
	v_cvt_pk_f16_f32 v93, v92, v93
	v_mul_f32_e32 v92, v87, v87
	v_pk_add_f32 v[94:95], v[82:83], v[94:95]
	v_fmac_f32_e32 v92, v86, v86
	v_mul_f32_e32 v82, v95, v95
	v_fmac_f32_e32 v92, v88, v88
	v_pk_add_f32 v[84:85], v[84:85], v[96:97]
	v_fmac_f32_e32 v82, v94, v94
	v_add_f32_e32 v110, v124, v110
	v_fmac_f32_e32 v92, v89, v89
	v_fmac_f32_e32 v82, v84, v84
	v_add_f32_e32 v92, v110, v92
	v_fmac_f32_e32 v82, v85, v85
	v_add_f32_e32 v82, v92, v82
	ds_bpermute_b32 v83, v161, v82
	v_cvt_pk_f16_f32 v92, v90, v91
	v_cvt_pk_f16_f32 v89, v88, v89
	v_cvt_pk_f16_f32 v88, v86, v87
	v_cvt_pk_f16_f32 v85, v84, v85
	s_waitcnt lgkmcnt(0)
	v_add_f32_e32 v82, v82, v83
	ds_bpermute_b32 v83, v162, v82
	v_cvt_pk_f16_f32 v84, v94, v95
	global_store_dwordx2 v[116:117], v[92:93], off offset:32
	global_store_dwordx2 v[116:117], v[88:89], off offset:256
	global_store_dwordx2 v[116:117], v[84:85], off offset:288
	s_and_saveexec_b64 s[4:5], s[6:7]
	s_cbranch_execz .LBB0_1379
	v_lshl_add_u64 v[84:85], v[114:115], 2, s[12:13]
	s_waitcnt lgkmcnt(0)
	v_add_f32_e32 v82, v82, v83
	global_atomic_add_f32 v[84:85], v82, off
;     __device__ __forceinline__ void operator()(const f32x4 (&acc)[2][2][4][2], const Unit& u, int wr, int wc, int fr, int fq) const {
;     ...
; #pragma unroll
;         for (int g = 0; g < 8; ++g) {
;             const int ai = g >> 2, m = g & 3;
;             const int r = row0 + ai * HALF + m * 16; float ss = 0.f;
;             if (g < 7) { const int rn = row0 + ((g + 1) >> 2) * HALF + ((g + 1) & 3) * 16;
; #pragma unroll
;                 for (int bj = 0; bj < 2; ++bj)
; #pragma unroll
;                     for (int n = 0; n < 2; ++n) hnx[bj][n] = *(const h16x4*)(HB + (size_t)rn * D + col0 + bj * HALF + n * 16); }
; #pragma unroll
;             for (int bj = 0; bj < 2; ++bj)
; #pragma unroll
;                 for (int n = 0; n < 2; ++n) {
;                     const size_t o = (size_t)r * D + col0 + bj * HALF + n * 16;
;                     f32x4 hv; hv[0] = (float)hin[bj][n][0]; hv[1] = (float)hin[bj][n][1]; hv[2] = (float)hin[bj][n][2]; hv[3] = (float)hin[bj][n][3];
;                     hv += acc[ai][bj][m][n];
;                     ss += hv[0] * hv[0] + hv[1] * hv[1] + hv[2] * hv[2] + hv[3] * hv[3];
;                     if (OUT != nullptr) *(f32x4*)(OUT + o) = hv;
;                     else { h16x4 hh; hh[0] = (h16)hv[0]; hh[1] = (h16)hv[1]; hh[2] = (h16)hv[2]; hh[3] = (h16)hv[3]; *(h16x4*)(HB + o) = hh; }
;                 }
;             ss += __shfl_xor(ss, 16); ss += __shfl_xor(ss, 32);
;             if (fq == 0) atomicAdd(rsq_next + r, ss);
.LBB0_1379:
	s_or_b64 exec, exec, s[4:5]
	v_add_u32_e32 v82, 0x80, v138
	s_waitcnt lgkmcnt(0)
	v_ashrrev_i32_e32 v83, 31, v82
	v_lshlrev_b64 v[84:85], 11, v[82:83]
	v_lshl_add_u64 v[84:85], s[10:11], 0, v[84:85]
	v_lshl_add_u64 v[84:85], v[136:137], 1, v[84:85]
	s_waitcnt vmcnt(27)
	v_mov_b32_e32 v92, v192
	v_mov_b32_e32 v93, v193
	v_mov_b32_e32 v90, v194
	v_mov_b32_e32 v91, v195
	v_mov_b32_e32 v88, v196
	v_mov_b32_e32 v89, v197
	v_mov_b32_e32 v86, v198
	v_mov_b32_e32 v87, v199
	s_nop 0
	v_cvt_f32_f16_sdwa v95, v108 dst_sel:DWORD dst_unused:UNUSED_PAD src0_sel:WORD_1
	v_cvt_f32_f16_e32 v94, v108
	v_cvt_f32_f16_sdwa v97, v109 dst_sel:DWORD dst_unused:UNUSED_PAD src0_sel:WORD_1
	v_cvt_f32_f16_e32 v96, v109
	v_pk_add_f32 v[78:79], v[78:79], v[94:95]
	s_nop 0
	v_mul_f32_e32 v108, v79, v79
	v_pk_add_f32 v[80:81], v[80:81], v[96:97]
	v_fmac_f32_e32 v108, v78, v78
	v_fmac_f32_e32 v108, v80, v80
	v_fmac_f32_e32 v108, v81, v81
	v_cvt_pk_f16_f32 v81, v80, v81
	s_nop 0
	v_cvt_f32_f16_sdwa v95, v106 dst_sel:DWORD dst_unused:UNUSED_PAD src0_sel:WORD_1
	v_cvt_f32_f16_e32 v94, v106
	v_cvt_pk_f16_f32 v80, v78, v79
	s_nop 0
	v_cvt_f32_f16_sdwa v79, v104 dst_sel:DWORD dst_unused:UNUSED_PAD src0_sel:WORD_1
	v_cvt_f32_f16_e32 v78, v104
	v_cvt_f32_f16_sdwa v97, v107 dst_sel:DWORD dst_unused:UNUSED_PAD src0_sel:WORD_1
	v_cvt_f32_f16_e32 v96, v107
	global_store_dwordx2 v[100:101], v[80:81], off
	v_cvt_f32_f16_sdwa v81, v105 dst_sel:DWORD dst_unused:UNUSED_PAD src0_sel:WORD_1
	v_cvt_f32_f16_e32 v80, v105
	v_pk_add_f32 v[74:75], v[74:75], v[94:95]
	v_pk_add_f32 v[70:71], v[70:71], v[78:79]
	s_nop 0
	v_cvt_f32_f16_sdwa v79, v102 dst_sel:DWORD dst_unused:UNUSED_PAD src0_sel:WORD_1
	v_cvt_f32_f16_e32 v78, v102
	v_mul_f32_e32 v94, v75, v75
	v_pk_add_f32 v[76:77], v[76:77], v[96:97]
	v_fmac_f32_e32 v94, v74, v74
	v_pk_add_f32 v[72:73], v[72:73], v[80:81]
	v_cvt_f32_f16_sdwa v81, v103 dst_sel:DWORD dst_unused:UNUSED_PAD src0_sel:WORD_1
	v_cvt_f32_f16_e32 v80, v103
	v_fmac_f32_e32 v94, v76, v76
	v_fmac_f32_e32 v94, v77, v77
	v_cvt_pk_f16_f32 v77, v76, v77
	v_mul_f32_e32 v76, v71, v71
	v_pk_add_f32 v[78:79], v[66:67], v[78:79]
	v_fmac_f32_e32 v76, v70, v70
	v_mul_f32_e32 v66, v79, v79
	v_fmac_f32_e32 v76, v72, v72
	v_pk_add_f32 v[68:69], v[68:69], v[80:81]
	v_fmac_f32_e32 v66, v78, v78
	v_add_f32_e32 v94, v108, v94
	v_fmac_f32_e32 v76, v73, v73
	v_fmac_f32_e32 v66, v68, v68
	v_add_f32_e32 v76, v94, v76
	v_fmac_f32_e32 v66, v69, v69
	v_add_f32_e32 v66, v76, v66
	ds_bpermute_b32 v67, v161, v66
	v_cvt_pk_f16_f32 v76, v74, v75
	v_cvt_pk_f16_f32 v73, v72, v73
	v_cvt_pk_f16_f32 v72, v70, v71
	v_cvt_pk_f16_f32 v69, v68, v69
	s_waitcnt lgkmcnt(0)
	v_add_f32_e32 v66, v66, v67
	ds_bpermute_b32 v67, v162, v66
	v_cvt_pk_f16_f32 v68, v78, v79
	global_store_dwordx2 v[100:101], v[76:77], off offset:32
	global_store_dwordx2 v[100:101], v[72:73], off offset:256
	global_store_dwordx2 v[100:101], v[68:69], off offset:288
	s_and_saveexec_b64 s[4:5], s[6:7]
	s_cbranch_execz .LBB0_1381
	v_lshl_add_u64 v[68:69], v[98:99], 2, s[12:13]
	s_waitcnt lgkmcnt(0)
	v_add_f32_e32 v66, v66, v67
	global_atomic_add_f32 v[68:69], v66, off
.LBB0_1381:
	s_or_b64 exec, exec, s[4:5]
	v_or_b32_e32 v66, 16, v82
	s_waitcnt lgkmcnt(0)
	v_ashrrev_i32_e32 v67, 31, v66
	v_lshlrev_b64 v[68:69], 11, v[66:67]
	v_lshl_add_u64 v[68:69], s[10:11], 0, v[68:69]
	v_lshl_add_u64 v[68:69], v[136:137], 1, v[68:69]
	s_waitcnt vmcnt(28)
	v_mov_b32_e32 v76, v200
	v_mov_b32_e32 v77, v201
	v_mov_b32_e32 v74, v202
	v_mov_b32_e32 v75, v203
	v_mov_b32_e32 v72, v204
	v_mov_b32_e32 v73, v205
	v_mov_b32_e32 v70, v206
	v_mov_b32_e32 v71, v207
	s_nop 0
	v_cvt_f32_f16_sdwa v79, v92 dst_sel:DWORD dst_unused:UNUSED_PAD src0_sel:WORD_1
	v_cvt_f32_f16_e32 v78, v92
	v_cvt_f32_f16_sdwa v81, v93 dst_sel:DWORD dst_unused:UNUSED_PAD src0_sel:WORD_1
	v_cvt_f32_f16_e32 v80, v93
	v_pk_add_f32 v[62:63], v[62:63], v[78:79]
	s_nop 0
	v_mul_f32_e32 v92, v63, v63
	v_pk_add_f32 v[64:65], v[64:65], v[80:81]
	v_fmac_f32_e32 v92, v62, v62
	v_fmac_f32_e32 v92, v64, v64
	v_fmac_f32_e32 v92, v65, v65
	v_cvt_pk_f16_f32 v65, v64, v65
	s_nop 0
	v_cvt_f32_f16_sdwa v79, v90 dst_sel:DWORD dst_unused:UNUSED_PAD src0_sel:WORD_1
	v_cvt_f32_f16_e32 v78, v90
	v_cvt_pk_f16_f32 v64, v62, v63
	s_nop 0
	v_cvt_f32_f16_sdwa v63, v88 dst_sel:DWORD dst_unused:UNUSED_PAD src0_sel:WORD_1
	v_cvt_f32_f16_e32 v62, v88
	v_cvt_f32_f16_sdwa v81, v91 dst_sel:DWORD dst_unused:UNUSED_PAD src0_sel:WORD_1
	v_cvt_f32_f16_e32 v80, v91
	global_store_dwordx2 v[84:85], v[64:65], off
	v_cvt_f32_f16_sdwa v65, v89 dst_sel:DWORD dst_unused:UNUSED_PAD src0_sel:WORD_1
	v_cvt_f32_f16_e32 v64, v89
	v_pk_add_f32 v[58:59], v[58:59], v[78:79]
	v_pk_add_f32 v[54:55], v[54:55], v[62:63]
	s_nop 0
	v_cvt_f32_f16_sdwa v63, v86 dst_sel:DWORD dst_unused:UNUSED_PAD src0_sel:WORD_1
	v_cvt_f32_f16_e32 v62, v86
	v_mul_f32_e32 v78, v59, v59
	v_pk_add_f32 v[60:61], v[60:61], v[80:81]
	v_fmac_f32_e32 v78, v58, v58
	v_pk_add_f32 v[56:57], v[56:57], v[64:65]
	v_cvt_f32_f16_sdwa v65, v87 dst_sel:DWORD dst_unused:UNUSED_PAD src0_sel:WORD_1
	v_cvt_f32_f16_e32 v64, v87
	v_fmac_f32_e32 v78, v60, v60
	v_fmac_f32_e32 v78, v61, v61
	v_cvt_pk_f16_f32 v61, v60, v61
	v_mul_f32_e32 v60, v55, v55
	v_pk_add_f32 v[62:63], v[50:51], v[62:63]
	v_fmac_f32_e32 v60, v54, v54
	v_mul_f32_e32 v50, v63, v63
	v_fmac_f32_e32 v60, v56, v56
	v_pk_add_f32 v[52:53], v[52:53], v[64:65]
	v_fmac_f32_e32 v50, v62, v62
	v_add_f32_e32 v78, v92, v78
	v_fmac_f32_e32 v60, v57, v57
	v_fmac_f32_e32 v50, v52, v52
	v_add_f32_e32 v60, v78, v60
	v_fmac_f32_e32 v50, v53, v53
	v_add_f32_e32 v50, v60, v50
	ds_bpermute_b32 v51, v161, v50
	v_cvt_pk_f16_f32 v60, v58, v59
	v_cvt_pk_f16_f32 v57, v56, v57
	v_cvt_pk_f16_f32 v56, v54, v55
	v_cvt_pk_f16_f32 v53, v52, v53
	s_waitcnt lgkmcnt(0)
	v_add_f32_e32 v50, v50, v51
	ds_bpermute_b32 v51, v162, v50
	v_cvt_pk_f16_f32 v52, v62, v63
	global_store_dwordx2 v[84:85], v[60:61], off offset:32
	global_store_dwordx2 v[84:85], v[56:57], off offset:256
	global_store_dwordx2 v[84:85], v[52:53], off offset:288
	s_and_saveexec_b64 s[4:5], s[6:7]
	s_cbranch_execz .LBB0_1383
	v_lshl_add_u64 v[52:53], v[82:83], 2, s[12:13]
	s_waitcnt lgkmcnt(0)
	v_add_f32_e32 v50, v50, v51
	global_atomic_add_f32 v[52:53], v50, off
;     __device__ __forceinline__ void operator()(const f32x4 (&acc)[2][2][4][2], const Unit& u, int wr, int wc, int fr, int fq) const {
;     ...
; #pragma unroll
;         for (int g = 0; g < 8; ++g) {
;             const int ai = g >> 2, m = g & 3;
;             const int r = row0 + ai * HALF + m * 16; float ss = 0.f;
;             if (g < 7) { const int rn = row0 + ((g + 1) >> 2) * HALF + ((g + 1) & 3) * 16;
; #pragma unroll
;                 for (int bj = 0; bj < 2; ++bj)
; #pragma unroll
;                     for (int n = 0; n < 2; ++n) hnx[bj][n] = *(const h16x4*)(HB + (size_t)rn * D + col0 + bj * HALF + n * 16); }
; #pragma unroll
;             for (int bj = 0; bj < 2; ++bj)
; #pragma unroll
;                 for (int n = 0; n < 2; ++n) {
;                     const size_t o = (size_t)r * D + col0 + bj * HALF + n * 16;
;                     f32x4 hv; hv[0] = (float)hin[bj][n][0]; hv[1] = (float)hin[bj][n][1]; hv[2] = (float)hin[bj][n][2]; hv[3] = (float)hin[bj][n][3];
;                     hv += acc[ai][bj][m][n];
;                     ss += hv[0] * hv[0] + hv[1] * hv[1] + hv[2] * hv[2] + hv[3] * hv[3];
;                     if (OUT != nullptr) *(f32x4*)(OUT + o) = hv;
;                     else { h16x4 hh; hh[0] = (h16)hv[0]; hh[1] = (h16)hv[1]; hh[2] = (h16)hv[2]; hh[3] = (h16)hv[3]; *(h16x4*)(HB + o) = hh; }
;                 }
;             ss += __shfl_xor(ss, 16); ss += __shfl_xor(ss, 32);
;             if (fq == 0) atomicAdd(rsq_next + r, ss);
.LBB0_1383:
	s_or_b64 exec, exec, s[4:5]
	v_or_b32_e32 v50, 32, v82
	s_waitcnt lgkmcnt(0)
	v_ashrrev_i32_e32 v51, 31, v50
	v_lshlrev_b64 v[52:53], 11, v[50:51]
	v_lshl_add_u64 v[52:53], s[10:11], 0, v[52:53]
	v_lshl_add_u64 v[52:53], v[136:137], 1, v[52:53]
	s_waitcnt vmcnt(29)
	v_mov_b32_e32 v60, v208
	v_mov_b32_e32 v61, v209
	v_mov_b32_e32 v58, v210
	v_mov_b32_e32 v59, v211
	v_mov_b32_e32 v56, v212
	v_mov_b32_e32 v57, v213
	v_mov_b32_e32 v54, v232
	v_mov_b32_e32 v55, v233
	s_nop 0
	v_cvt_f32_f16_sdwa v63, v76 dst_sel:DWORD dst_unused:UNUSED_PAD src0_sel:WORD_1
	v_cvt_f32_f16_e32 v62, v76
	v_cvt_f32_f16_sdwa v65, v77 dst_sel:DWORD dst_unused:UNUSED_PAD src0_sel:WORD_1
	v_cvt_f32_f16_e32 v64, v77
	v_pk_add_f32 v[46:47], v[46:47], v[62:63]
	s_nop 0
	v_mul_f32_e32 v76, v47, v47
	v_pk_add_f32 v[48:49], v[48:49], v[64:65]
	v_fmac_f32_e32 v76, v46, v46
	v_fmac_f32_e32 v76, v48, v48
	v_fmac_f32_e32 v76, v49, v49
	v_cvt_pk_f16_f32 v49, v48, v49
	s_nop 0
	v_cvt_f32_f16_sdwa v63, v74 dst_sel:DWORD dst_unused:UNUSED_PAD src0_sel:WORD_1
	v_cvt_f32_f16_e32 v62, v74
	v_cvt_pk_f16_f32 v48, v46, v47
	s_nop 0
	v_cvt_f32_f16_sdwa v47, v72 dst_sel:DWORD dst_unused:UNUSED_PAD src0_sel:WORD_1
	v_cvt_f32_f16_e32 v46, v72
	v_cvt_f32_f16_sdwa v65, v75 dst_sel:DWORD dst_unused:UNUSED_PAD src0_sel:WORD_1
	v_cvt_f32_f16_e32 v64, v75
	global_store_dwordx2 v[68:69], v[48:49], off
	v_cvt_f32_f16_sdwa v49, v73 dst_sel:DWORD dst_unused:UNUSED_PAD src0_sel:WORD_1
	v_cvt_f32_f16_e32 v48, v73
	v_pk_add_f32 v[42:43], v[42:43], v[62:63]
	v_pk_add_f32 v[38:39], v[38:39], v[46:47]
	s_nop 0
	v_cvt_f32_f16_sdwa v47, v70 dst_sel:DWORD dst_unused:UNUSED_PAD src0_sel:WORD_1
	v_cvt_f32_f16_e32 v46, v70
	v_mul_f32_e32 v62, v43, v43
	v_pk_add_f32 v[44:45], v[44:45], v[64:65]
	v_fmac_f32_e32 v62, v42, v42
	v_pk_add_f32 v[40:41], v[40:41], v[48:49]
	v_cvt_f32_f16_sdwa v49, v71 dst_sel:DWORD dst_unused:UNUSED_PAD src0_sel:WORD_1
	v_cvt_f32_f16_e32 v48, v71
	v_fmac_f32_e32 v62, v44, v44
	v_fmac_f32_e32 v62, v45, v45
	v_cvt_pk_f16_f32 v45, v44, v45
	v_mul_f32_e32 v44, v39, v39
	v_pk_add_f32 v[46:47], v[34:35], v[46:47]
	v_fmac_f32_e32 v44, v38, v38
	v_mul_f32_e32 v34, v47, v47
	v_fmac_f32_e32 v44, v40, v40
	v_pk_add_f32 v[36:37], v[36:37], v[48:49]
	v_fmac_f32_e32 v34, v46, v46
	v_add_f32_e32 v62, v76, v62
	v_fmac_f32_e32 v44, v41, v41
	v_fmac_f32_e32 v34, v36, v36
	v_add_f32_e32 v44, v62, v44
	v_fmac_f32_e32 v34, v37, v37
	v_add_f32_e32 v34, v44, v34
	ds_bpermute_b32 v35, v161, v34
	v_cvt_pk_f16_f32 v44, v42, v43
	v_cvt_pk_f16_f32 v41, v40, v41
	v_cvt_pk_f16_f32 v40, v38, v39
	v_cvt_pk_f16_f32 v37, v36, v37
	s_waitcnt lgkmcnt(0)
	v_add_f32_e32 v34, v34, v35
	ds_bpermute_b32 v35, v162, v34
	v_cvt_pk_f16_f32 v36, v46, v47
	global_store_dwordx2 v[68:69], v[44:45], off offset:32
	global_store_dwordx2 v[68:69], v[40:41], off offset:256
	global_store_dwordx2 v[68:69], v[36:37], off offset:288
	s_and_saveexec_b64 s[4:5], s[6:7]
	s_cbranch_execz .LBB0_1385
	v_lshl_add_u64 v[36:37], v[66:67], 2, s[12:13]
	s_waitcnt lgkmcnt(0)
	v_add_f32_e32 v34, v34, v35
	global_atomic_add_f32 v[36:37], v34, off
;     __device__ __forceinline__ void operator()(const f32x4 (&acc)[2][2][4][2], const Unit& u, int wr, int wc, int fr, int fq) const {
;     ...
; #pragma unroll
;         for (int g = 0; g < 8; ++g) {
;             const int ai = g >> 2, m = g & 3;
;             const int r = row0 + ai * HALF + m * 16; float ss = 0.f;
;             if (g < 7) { const int rn = row0 + ((g + 1) >> 2) * HALF + ((g + 1) & 3) * 16;
; #pragma unroll
;                 for (int bj = 0; bj < 2; ++bj)
; #pragma unroll
;                     for (int n = 0; n < 2; ++n) hnx[bj][n] = *(const h16x4*)(HB + (size_t)rn * D + col0 + bj * HALF + n * 16); }
; #pragma unroll
;             for (int bj = 0; bj < 2; ++bj)
; #pragma unroll
;                 for (int n = 0; n < 2; ++n) {
;                     const size_t o = (size_t)r * D + col0 + bj * HALF + n * 16;
;                     f32x4 hv; hv[0] = (float)hin[bj][n][0]; hv[1] = (float)hin[bj][n][1]; hv[2] = (float)hin[bj][n][2]; hv[3] = (float)hin[bj][n][3];
;                     hv += acc[ai][bj][m][n];
;                     ss += hv[0] * hv[0] + hv[1] * hv[1] + hv[2] * hv[2] + hv[3] * hv[3];
;                     if (OUT != nullptr) *(f32x4*)(OUT + o) = hv;
;                     else { h16x4 hh; hh[0] = (h16)hv[0]; hh[1] = (h16)hv[1]; hh[2] = (h16)hv[2]; hh[3] = (h16)hv[3]; *(h16x4*)(HB + o) = hh; }
;                 }
;             ss += __shfl_xor(ss, 16); ss += __shfl_xor(ss, 32);
;             if (fq == 0) atomicAdd(rsq_next + r, ss);
.LBB0_1385:
	s_or_b64 exec, exec, s[4:5]
	v_or_b32_e32 v34, 48, v82
	s_waitcnt lgkmcnt(0)
	v_ashrrev_i32_e32 v35, 31, v34
	v_lshlrev_b64 v[36:37], 11, v[34:35]
	v_lshl_add_u64 v[36:37], s[10:11], 0, v[36:37]
	v_lshl_add_u64 v[36:37], v[136:137], 1, v[36:37]
	s_waitcnt vmcnt(30)
	v_mov_b32_e32 v44, v234
	v_mov_b32_e32 v45, v235
	v_mov_b32_e32 v42, v236
	v_mov_b32_e32 v43, v237
	v_mov_b32_e32 v40, v238
	v_mov_b32_e32 v41, v239
	v_mov_b32_e32 v38, v240
	v_mov_b32_e32 v39, v241
	s_nop 0
	v_cvt_f32_f16_sdwa v47, v60 dst_sel:DWORD dst_unused:UNUSED_PAD src0_sel:WORD_1
	v_cvt_f32_f16_e32 v46, v60
	v_cvt_f32_f16_sdwa v49, v61 dst_sel:DWORD dst_unused:UNUSED_PAD src0_sel:WORD_1
	v_cvt_f32_f16_e32 v48, v61
	v_pk_add_f32 v[30:31], v[30:31], v[46:47]
	s_nop 0
	v_mul_f32_e32 v60, v31, v31
	v_pk_add_f32 v[32:33], v[32:33], v[48:49]
	v_fmac_f32_e32 v60, v30, v30
	v_fmac_f32_e32 v60, v32, v32
	v_fmac_f32_e32 v60, v33, v33
	v_cvt_pk_f16_f32 v33, v32, v33
	s_nop 0
	v_cvt_f32_f16_sdwa v47, v58 dst_sel:DWORD dst_unused:UNUSED_PAD src0_sel:WORD_1
	v_cvt_f32_f16_e32 v46, v58
	v_cvt_pk_f16_f32 v32, v30, v31
	s_nop 0
	v_cvt_f32_f16_sdwa v31, v56 dst_sel:DWORD dst_unused:UNUSED_PAD src0_sel:WORD_1
	v_cvt_f32_f16_e32 v30, v56
	v_cvt_f32_f16_sdwa v49, v59 dst_sel:DWORD dst_unused:UNUSED_PAD src0_sel:WORD_1
	v_cvt_f32_f16_e32 v48, v59
	global_store_dwordx2 v[52:53], v[32:33], off
	v_cvt_f32_f16_sdwa v33, v57 dst_sel:DWORD dst_unused:UNUSED_PAD src0_sel:WORD_1
	v_cvt_f32_f16_e32 v32, v57
	v_pk_add_f32 v[26:27], v[26:27], v[46:47]
	v_pk_add_f32 v[22:23], v[22:23], v[30:31]
	s_nop 0
	v_cvt_f32_f16_sdwa v31, v54 dst_sel:DWORD dst_unused:UNUSED_PAD src0_sel:WORD_1
	v_cvt_f32_f16_e32 v30, v54
	v_mul_f32_e32 v46, v27, v27
	v_pk_add_f32 v[28:29], v[28:29], v[48:49]
	v_fmac_f32_e32 v46, v26, v26
	v_pk_add_f32 v[24:25], v[24:25], v[32:33]
	v_cvt_f32_f16_sdwa v33, v55 dst_sel:DWORD dst_unused:UNUSED_PAD src0_sel:WORD_1
	v_cvt_f32_f16_e32 v32, v55
	v_fmac_f32_e32 v46, v28, v28
	v_fmac_f32_e32 v46, v29, v29
	v_cvt_pk_f16_f32 v29, v28, v29
	v_mul_f32_e32 v28, v23, v23
	v_pk_add_f32 v[30:31], v[18:19], v[30:31]
	v_fmac_f32_e32 v28, v22, v22
	v_mul_f32_e32 v18, v31, v31
	v_fmac_f32_e32 v28, v24, v24
	v_pk_add_f32 v[20:21], v[20:21], v[32:33]
	v_fmac_f32_e32 v18, v30, v30
	v_add_f32_e32 v46, v60, v46
	v_fmac_f32_e32 v28, v25, v25
	v_fmac_f32_e32 v18, v20, v20
	v_add_f32_e32 v28, v46, v28
	v_fmac_f32_e32 v18, v21, v21
	v_add_f32_e32 v18, v28, v18
	ds_bpermute_b32 v19, v161, v18
	v_cvt_pk_f16_f32 v28, v26, v27
	v_cvt_pk_f16_f32 v25, v24, v25
	v_cvt_pk_f16_f32 v24, v22, v23
	v_cvt_pk_f16_f32 v21, v20, v21
	s_waitcnt lgkmcnt(0)
	v_add_f32_e32 v18, v18, v19
	ds_bpermute_b32 v19, v162, v18
	v_cvt_pk_f16_f32 v20, v30, v31
	global_store_dwordx2 v[52:53], v[28:29], off offset:32
	global_store_dwordx2 v[52:53], v[24:25], off offset:256
	global_store_dwordx2 v[52:53], v[20:21], off offset:288
	s_and_saveexec_b64 s[4:5], s[6:7]
	s_cbranch_execz .LBB0_1387
	v_lshl_add_u64 v[20:21], v[50:51], 2, s[12:13]
	s_waitcnt lgkmcnt(0)
	v_add_f32_e32 v18, v18, v19
	global_atomic_add_f32 v[20:21], v18, off
.LBB0_1387:
	s_or_b64 exec, exec, s[4:5]
	s_waitcnt lgkmcnt(0)
	v_cvt_f32_f16_sdwa v19, v44 dst_sel:DWORD dst_unused:UNUSED_PAD src0_sel:WORD_1
	v_cvt_f32_f16_e32 v18, v44
	v_cvt_f32_f16_sdwa v21, v45 dst_sel:DWORD dst_unused:UNUSED_PAD src0_sel:WORD_1
	v_cvt_f32_f16_e32 v20, v45
	v_pk_add_f32 v[14:15], v[14:15], v[18:19]
	s_nop 0
	v_mul_f32_e32 v22, v15, v15
	v_pk_add_f32 v[16:17], v[16:17], v[20:21]
	v_fmac_f32_e32 v22, v14, v14
	v_fmac_f32_e32 v22, v16, v16
	v_fmac_f32_e32 v22, v17, v17
	v_cvt_pk_f16_f32 v17, v16, v17
	s_nop 0
	v_cvt_f32_f16_sdwa v19, v42 dst_sel:DWORD dst_unused:UNUSED_PAD src0_sel:WORD_1
	v_cvt_f32_f16_e32 v18, v42
	v_cvt_pk_f16_f32 v16, v14, v15
	s_nop 0
	v_cvt_f32_f16_sdwa v15, v40 dst_sel:DWORD dst_unused:UNUSED_PAD src0_sel:WORD_1
	v_cvt_f32_f16_e32 v14, v40
	v_cvt_f32_f16_sdwa v21, v43 dst_sel:DWORD dst_unused:UNUSED_PAD src0_sel:WORD_1
	v_cvt_f32_f16_e32 v20, v43
	global_store_dwordx2 v[36:37], v[16:17], off
	v_cvt_f32_f16_sdwa v17, v41 dst_sel:DWORD dst_unused:UNUSED_PAD src0_sel:WORD_1
	v_cvt_f32_f16_e32 v16, v41
	v_pk_add_f32 v[10:11], v[10:11], v[18:19]
	v_pk_add_f32 v[6:7], v[6:7], v[14:15]
	s_nop 0
	v_cvt_f32_f16_sdwa v15, v38 dst_sel:DWORD dst_unused:UNUSED_PAD src0_sel:WORD_1
	v_cvt_f32_f16_e32 v14, v38
	v_mul_f32_e32 v18, v11, v11
	v_pk_add_f32 v[12:13], v[12:13], v[20:21]
	v_fmac_f32_e32 v18, v10, v10
	v_pk_add_f32 v[8:9], v[8:9], v[16:17]
	v_cvt_f32_f16_sdwa v17, v39 dst_sel:DWORD dst_unused:UNUSED_PAD src0_sel:WORD_1
	v_cvt_f32_f16_e32 v16, v39
	v_fmac_f32_e32 v18, v12, v12
	v_fmac_f32_e32 v18, v13, v13
	v_cvt_pk_f16_f32 v13, v12, v13
	v_mul_f32_e32 v12, v7, v7
	v_pk_add_f32 v[14:15], v[2:3], v[14:15]
	v_fmac_f32_e32 v12, v6, v6
	v_mul_f32_e32 v2, v15, v15
	v_fmac_f32_e32 v12, v8, v8
	v_pk_add_f32 v[4:5], v[4:5], v[16:17]
	v_fmac_f32_e32 v2, v14, v14
	v_add_f32_e32 v18, v22, v18
	v_fmac_f32_e32 v12, v9, v9
	v_fmac_f32_e32 v2, v4, v4
	v_add_f32_e32 v12, v18, v12
	v_fmac_f32_e32 v2, v5, v5
	v_add_f32_e32 v2, v12, v2
	ds_bpermute_b32 v3, v161, v2
	v_cvt_pk_f16_f32 v12, v10, v11
	v_cvt_pk_f16_f32 v9, v8, v9
	v_cvt_pk_f16_f32 v8, v6, v7
	v_cvt_pk_f16_f32 v5, v4, v5
	s_waitcnt lgkmcnt(0)
	v_add_f32_e32 v2, v2, v3
	ds_bpermute_b32 v3, v162, v2
	v_cvt_pk_f16_f32 v4, v14, v15
	global_store_dwordx2 v[36:37], v[12:13], off offset:32
	global_store_dwordx2 v[36:37], v[8:9], off offset:256
	global_store_dwordx2 v[36:37], v[4:5], off offset:288
	s_and_saveexec_b64 s[4:5], s[6:7]
	s_cbranch_execz .LBB0_1364
	v_lshl_add_u64 v[4:5], v[34:35], 2, s[12:13]
	s_waitcnt lgkmcnt(0)
	v_add_f32_e32 v2, v2, v3
	global_atomic_add_f32 v[4:5], v2, off
	s_branch .LBB0_1364
